# FFN-up conv groups start from one v_fma (bias + centre tap) instead of v_mov + trailing v_fmac
# speedup vs baseline: 1.0115x; 1.0115x over previous
; #define PG8_LAS __attribute__((address_space(3)))
;     __device__ __forceinline__ void operator()(f32x4 (&acc)[2][2][4][2], const Unit& u, int ui, int wr, int wc, int fr_, int fq_) const {
;     ...
;             for (int m = 0; m < 4; ++m) { const float r = rtab[ui * 256 + ai * HALF + wr * 64 + m * 16 + fr];
; #pragma unroll
;                 for (int bj = 0; bj < 2; ++bj)
; #pragma unroll
;                     for (int n = 0; n < 2; ++n) acc[ai][bj][m][n] = acc[ai][bj][m][n] * r; }
;     ...
;                 for (int ai = 0; ai < 2; ++ai) { const int kb = 2 * ai + wr;
;                     f32x4 c62 = (f32x4){0.f, 0.f, 0.f, 0.f}, c63 = c62;
;                     if (kb > 0) { c62 = *(const PG8_LAS f32x4*)(exch + (((kb - 1) * 2 + 0) * 256 + bj * HALF + 32 * wc + 8 * fq + 4 * n)); c63 = *(const PG8_LAS f32x4*)(exch + (((kb - 1) * 2 + 1) * 256 + bj * HALF + 32 * wc + 8 * fq + 4 * n)); }
; #pragma unroll
;                     for (int m = 3; m >= 0; --m) { f32x4 cur = acc[ai][bj][m][n], res;
; #pragma unroll
;                         for (int j = 0; j < 4; ++j) { const float c = cur[j]; const float pv = (m > 0) ? acc[ai][bj][m > 0 ? m - 1 : 0][n][j] : (fr == 15 ? c63[j] : c62[j]); float t1, t2;
;                             asm volatile("s_nop 1\n\tv_mov_b32_dpp %0, %3 row_ror:1 row_mask:0xf bank_mask:0xf\n\tv_mov_b32_dpp %1, %3 row_ror:2 row_mask:0xf bank_mask:0xf\n\t"
;                                          "v_mov_b32_dpp %0, %2 row_shr:1 row_mask:0xf bank_mask:0xf\n\tv_mov_b32_dpp %1, %2 row_shr:2 row_mask:0xf bank_mask:0xf"
;                                          : "=&v"(t1), "=&v"(t2) : "v"(c), "v"(pv));
;                             res[j] = bb[j] + w0[j] * t2 + w1[j] * t1 + w2[j] * c; }
;                         asm volatile("" : "+v"(res[0]), "+v"(res[1]), "+v"(res[2]), "+v"(res[3]));
;                         acc[ai][bj][m][n] = res; } }
.LBB0_1186:
	v_pk_mul_f32 v[102:103], v[102:103], v[196:197] op_sel_hi:[1,0]
	v_pk_mul_f32 v[104:105], v[104:105], v[196:197] op_sel_hi:[1,0]
	v_pk_mul_f32 v[106:107], v[106:107], v[194:195] op_sel_hi:[1,0]
	s_waitcnt vmcnt(0)
	v_fma_f32 v211, v152, v130, v30
	v_fmac_f32_dpp v211, v152, v134 row_shr:2 row_mask:0xf bank_mask:0xf
	v_fmac_f32_dpp v211, v102, v134 row_shl:14 row_mask:0xf bank_mask:0xf
	v_fmac_f32_dpp v211, v152, v118 row_shr:1 row_mask:0xf bank_mask:0xf
	v_fmac_f32_dpp v211, v102, v118 row_shl:15 row_mask:0xf bank_mask:0xf
	v_pk_mul_f32 v[108:109], v[108:109], v[194:195] op_sel_hi:[1,0]
	v_fma_f32 v212, v153, v131, v31
	v_fmac_f32_dpp v212, v153, v135 row_shr:2 row_mask:0xf bank_mask:0xf
	v_fmac_f32_dpp v212, v103, v135 row_shl:14 row_mask:0xf bank_mask:0xf
	v_fmac_f32_dpp v212, v153, v119 row_shr:1 row_mask:0xf bank_mask:0xf
	v_fmac_f32_dpp v212, v103, v119 row_shl:15 row_mask:0xf bank_mask:0xf
	v_cmp_eq_u32_e64 s[8:9], 15, v210
	v_fma_f32 v152, v154, v132, v32
	v_fmac_f32_dpp v152, v154, v136 row_shr:2 row_mask:0xf bank_mask:0xf
	v_fmac_f32_dpp v152, v104, v136 row_shl:14 row_mask:0xf bank_mask:0xf
	v_fmac_f32_dpp v152, v154, v120 row_shr:1 row_mask:0xf bank_mask:0xf
	v_fmac_f32_dpp v152, v104, v120 row_shl:15 row_mask:0xf bank_mask:0xf
	s_andn2_b64 vcc, exec, s[40:41]
	v_fma_f32 v153, v155, v133, v33
	v_fmac_f32_dpp v153, v155, v137 row_shr:2 row_mask:0xf bank_mask:0xf
	v_fmac_f32_dpp v153, v105, v137 row_shl:14 row_mask:0xf bank_mask:0xf
	v_fmac_f32_dpp v153, v155, v121 row_shr:1 row_mask:0xf bank_mask:0xf
	v_fmac_f32_dpp v153, v105, v121 row_shl:15 row_mask:0xf bank_mask:0xf
	v_lshl_add_u32 v227, v143, 2, s86
	v_fma_f32 v213, v102, v130, v30
	v_fmac_f32_dpp v213, v102, v134 row_shr:2 row_mask:0xf bank_mask:0xf
	v_fmac_f32_dpp v213, v106, v134 row_shl:14 row_mask:0xf bank_mask:0xf
	v_fmac_f32_dpp v213, v102, v118 row_shr:1 row_mask:0xf bank_mask:0xf
	v_fmac_f32_dpp v213, v106, v118 row_shl:15 row_mask:0xf bank_mask:0xf
	v_mov_b32_e32 v143, 0
	v_fma_f32 v216, v103, v131, v31
	v_fmac_f32_dpp v216, v103, v135 row_shr:2 row_mask:0xf bank_mask:0xf
	v_fmac_f32_dpp v216, v107, v135 row_shl:14 row_mask:0xf bank_mask:0xf
	v_fmac_f32_dpp v216, v103, v119 row_shr:1 row_mask:0xf bank_mask:0xf
	v_fmac_f32_dpp v216, v107, v119 row_shl:15 row_mask:0xf bank_mask:0xf
	s_nop 0
	v_fma_f32 v154, v104, v132, v32
	v_fmac_f32_dpp v154, v104, v136 row_shr:2 row_mask:0xf bank_mask:0xf
	v_fmac_f32_dpp v154, v108, v136 row_shl:14 row_mask:0xf bank_mask:0xf
	v_fmac_f32_dpp v154, v104, v120 row_shr:1 row_mask:0xf bank_mask:0xf
	v_fmac_f32_dpp v154, v108, v120 row_shl:15 row_mask:0xf bank_mask:0xf
	v_fma_f32 v214, v105, v133, v33
	v_fmac_f32_dpp v214, v105, v137 row_shr:2 row_mask:0xf bank_mask:0xf
	v_fmac_f32_dpp v214, v109, v137 row_shl:14 row_mask:0xf bank_mask:0xf
	v_fmac_f32_dpp v214, v105, v121 row_shr:1 row_mask:0xf bank_mask:0xf
	v_fmac_f32_dpp v214, v109, v121 row_shl:15 row_mask:0xf bank_mask:0xf
	s_waitcnt lgkmcnt(0)
	v_cndmask_b32_e64 v105, v144, v148, s[8:9]
	v_fma_f32 v218, v106, v130, v30
	v_fmac_f32_dpp v218, v106, v134 row_shr:2 row_mask:0xf bank_mask:0xf
	v_fmac_f32_dpp v218, v138, v134 row_shl:14 row_mask:0xf bank_mask:0xf
	v_fmac_f32_dpp v218, v106, v118 row_shr:1 row_mask:0xf bank_mask:0xf
	v_fmac_f32_dpp v218, v138, v118 row_shl:15 row_mask:0xf bank_mask:0xf
	v_fma_f32 v220, v107, v131, v31
	v_fmac_f32_dpp v220, v107, v135 row_shr:2 row_mask:0xf bank_mask:0xf
	v_fmac_f32_dpp v220, v139, v135 row_shl:14 row_mask:0xf bank_mask:0xf
	v_fmac_f32_dpp v220, v107, v119 row_shr:1 row_mask:0xf bank_mask:0xf
	v_fmac_f32_dpp v220, v139, v119 row_shl:15 row_mask:0xf bank_mask:0xf
	v_fma_f32 v217, v108, v132, v32
	v_fmac_f32_dpp v217, v108, v136 row_shr:2 row_mask:0xf bank_mask:0xf
	v_fmac_f32_dpp v217, v140, v136 row_shl:14 row_mask:0xf bank_mask:0xf
	v_fmac_f32_dpp v217, v108, v120 row_shr:1 row_mask:0xf bank_mask:0xf
	v_fmac_f32_dpp v217, v140, v120 row_shl:15 row_mask:0xf bank_mask:0xf
	v_fma_f32 v219, v109, v133, v33
	v_fmac_f32_dpp v219, v109, v137 row_shr:2 row_mask:0xf bank_mask:0xf
	v_fmac_f32_dpp v219, v141, v137 row_shl:14 row_mask:0xf bank_mask:0xf
	v_fmac_f32_dpp v219, v109, v121 row_shr:1 row_mask:0xf bank_mask:0xf
	v_fmac_f32_dpp v219, v141, v121 row_shl:15 row_mask:0xf bank_mask:0xf
	v_cndmask_b32_e64 v104, v145, v149, s[8:9]
	v_fma_f32 v223, v138, v130, v30
	v_fmac_f32_dpp v223, v138, v134 row_shr:2 row_mask:0xf bank_mask:0xf
	v_fmac_f32_dpp v223, v105, v134 row_shl:14 row_mask:0xf bank_mask:0xf
	v_fmac_f32_dpp v223, v138, v118 row_shr:1 row_mask:0xf bank_mask:0xf
	v_fmac_f32_dpp v223, v105, v118 row_shl:15 row_mask:0xf bank_mask:0xf
	v_cndmask_b32_e64 v103, v146, v150, s[8:9]
	v_fma_f32 v224, v139, v131, v31
	v_fmac_f32_dpp v224, v139, v135 row_shr:2 row_mask:0xf bank_mask:0xf
	v_fmac_f32_dpp v224, v104, v135 row_shl:14 row_mask:0xf bank_mask:0xf
	v_fmac_f32_dpp v224, v139, v119 row_shr:1 row_mask:0xf bank_mask:0xf
	v_fmac_f32_dpp v224, v104, v119 row_shl:15 row_mask:0xf bank_mask:0xf
	v_cndmask_b32_e64 v102, v147, v151, s[8:9]
	v_fma_f32 v221, v140, v132, v32
	v_fmac_f32_dpp v221, v140, v136 row_shr:2 row_mask:0xf bank_mask:0xf
	v_fmac_f32_dpp v221, v103, v136 row_shl:14 row_mask:0xf bank_mask:0xf
	v_fmac_f32_dpp v221, v140, v120 row_shr:1 row_mask:0xf bank_mask:0xf
	v_fmac_f32_dpp v221, v103, v120 row_shl:15 row_mask:0xf bank_mask:0xf
	v_fma_f32 v222, v141, v133, v33
	v_fmac_f32_dpp v222, v141, v137 row_shr:2 row_mask:0xf bank_mask:0xf
	v_fmac_f32_dpp v222, v102, v137 row_shl:14 row_mask:0xf bank_mask:0xf
	v_fmac_f32_dpp v222, v141, v121 row_shr:1 row_mask:0xf bank_mask:0xf
	v_fmac_f32_dpp v222, v102, v121 row_shl:15 row_mask:0xf bank_mask:0xf
	v_cndmask_b32_e64 v102, 0, 1, s[40:41]
	v_cmp_ne_u32_e64 s[12:13], 1, v102
	v_mov_b32_e32 v144, 0
	v_mov_b32_e32 v145, 0
	v_mov_b32_e32 v102, 0
	v_mov_b32_e32 v103, 0
	v_mov_b32_e32 v104, 0
	v_mov_b32_e32 v105, 0
	s_cbranch_vccnz .LBB0_1188
	ds_read_b128 v[142:145], v227 offset:2048
	ds_read_b128 v[102:105], v227 offset:3072
; #define PG8_LAS __attribute__((address_space(3)))
;     __device__ __forceinline__ void operator()(f32x4 (&acc)[2][2][4][2], const Unit& u, int ui, int wr, int wc, int fr_, int fq_) const {
;     ...
;                 for (int ai = 0; ai < 2; ++ai) { const int kb = 2 * ai + wr;
;                     f32x4 c62 = (f32x4){0.f, 0.f, 0.f, 0.f}, c63 = c62;
;                     if (kb > 0) { c62 = *(const PG8_LAS f32x4*)(exch + (((kb - 1) * 2 + 0) * 256 + bj * HALF + 32 * wc + 8 * fq + 4 * n)); c63 = *(const PG8_LAS f32x4*)(exch + (((kb - 1) * 2 + 1) * 256 + bj * HALF + 32 * wc + 8 * fq + 4 * n)); }
; #pragma unroll
;                     for (int m = 3; m >= 0; --m) { f32x4 cur = acc[ai][bj][m][n], res;
; #pragma unroll
;                         for (int j = 0; j < 4; ++j) { const float c = cur[j]; const float pv = (m > 0) ? acc[ai][bj][m > 0 ? m - 1 : 0][n][j] : (fr == 15 ? c63[j] : c62[j]); float t1, t2;
;                             asm volatile("s_nop 1\n\tv_mov_b32_dpp %0, %3 row_ror:1 row_mask:0xf bank_mask:0xf\n\tv_mov_b32_dpp %1, %3 row_ror:2 row_mask:0xf bank_mask:0xf\n\t"
;                                          "v_mov_b32_dpp %0, %2 row_shr:1 row_mask:0xf bank_mask:0xf\n\tv_mov_b32_dpp %1, %2 row_shr:2 row_mask:0xf bank_mask:0xf"
;                                          : "=&v"(t1), "=&v"(t2) : "v"(c), "v"(pv));
;                             res[j] = bb[j] + w0[j] * t2 + w1[j] * t1 + w2[j] * c; }
;                         asm volatile("" : "+v"(res[0]), "+v"(res[1]), "+v"(res[2]), "+v"(res[3]));
;                         acc[ai][bj][m][n] = res; } }
.LBB0_1188:
	v_pk_mul_f32 v[46:47], v[46:47], v[188:189] op_sel_hi:[1,0]
	v_pk_mul_f32 v[48:49], v[48:49], v[188:189] op_sel_hi:[1,0]
	v_pk_mul_f32 v[90:91], v[90:91], v[190:191] op_sel_hi:[1,0]
	v_fma_f32 v139, v126, v130, v30
	v_fmac_f32_dpp v139, v126, v134 row_shr:2 row_mask:0xf bank_mask:0xf
	v_fmac_f32_dpp v139, v46, v134 row_shl:14 row_mask:0xf bank_mask:0xf
	v_fmac_f32_dpp v139, v126, v118 row_shr:1 row_mask:0xf bank_mask:0xf
	v_fmac_f32_dpp v139, v46, v118 row_shl:15 row_mask:0xf bank_mask:0xf
	v_fma_f32 v141, v127, v131, v31
	v_fmac_f32_dpp v141, v127, v135 row_shr:2 row_mask:0xf bank_mask:0xf
	v_fmac_f32_dpp v141, v47, v135 row_shl:14 row_mask:0xf bank_mask:0xf
	v_fmac_f32_dpp v141, v127, v119 row_shr:1 row_mask:0xf bank_mask:0xf
	v_fmac_f32_dpp v141, v47, v119 row_shl:15 row_mask:0xf bank_mask:0xf
	v_fma_f32 v138, v128, v132, v32
	v_fmac_f32_dpp v138, v128, v136 row_shr:2 row_mask:0xf bank_mask:0xf
	v_fmac_f32_dpp v138, v48, v136 row_shl:14 row_mask:0xf bank_mask:0xf
	v_fmac_f32_dpp v138, v128, v120 row_shr:1 row_mask:0xf bank_mask:0xf
	v_fmac_f32_dpp v138, v48, v120 row_shl:15 row_mask:0xf bank_mask:0xf
	v_fma_f32 v140, v129, v133, v33
	v_fmac_f32_dpp v140, v129, v137 row_shr:2 row_mask:0xf bank_mask:0xf
	v_fmac_f32_dpp v140, v49, v137 row_shl:14 row_mask:0xf bank_mask:0xf
	v_fmac_f32_dpp v140, v129, v121 row_shr:1 row_mask:0xf bank_mask:0xf
	v_fmac_f32_dpp v140, v49, v121 row_shl:15 row_mask:0xf bank_mask:0xf
	v_pk_mul_f32 v[92:93], v[92:93], v[190:191] op_sel_hi:[1,0]
	v_fma_f32 v147, v46, v130, v30
	v_fmac_f32_dpp v147, v46, v134 row_shr:2 row_mask:0xf bank_mask:0xf
	v_fmac_f32_dpp v147, v90, v134 row_shl:14 row_mask:0xf bank_mask:0xf
	v_fmac_f32_dpp v147, v46, v118 row_shr:1 row_mask:0xf bank_mask:0xf
	v_fmac_f32_dpp v147, v90, v118 row_shl:15 row_mask:0xf bank_mask:0xf
	v_pk_mul_f32 v[94:95], v[94:95], v[192:193] op_sel_hi:[1,0]
	v_fma_f32 v149, v47, v131, v31
	v_fmac_f32_dpp v149, v47, v135 row_shr:2 row_mask:0xf bank_mask:0xf
	v_fmac_f32_dpp v149, v91, v135 row_shl:14 row_mask:0xf bank_mask:0xf
	v_fmac_f32_dpp v149, v47, v119 row_shr:1 row_mask:0xf bank_mask:0xf
	v_fmac_f32_dpp v149, v91, v119 row_shl:15 row_mask:0xf bank_mask:0xf
	v_pk_mul_f32 v[96:97], v[96:97], v[192:193] op_sel_hi:[1,0]
	v_fma_f32 v146, v48, v132, v32
	v_fmac_f32_dpp v146, v48, v136 row_shr:2 row_mask:0xf bank_mask:0xf
	v_fmac_f32_dpp v146, v92, v136 row_shl:14 row_mask:0xf bank_mask:0xf
	v_fmac_f32_dpp v146, v48, v120 row_shr:1 row_mask:0xf bank_mask:0xf
	v_fmac_f32_dpp v146, v92, v120 row_shl:15 row_mask:0xf bank_mask:0xf
	v_fma_f32 v148, v49, v133, v33
	v_fmac_f32_dpp v148, v49, v137 row_shr:2 row_mask:0xf bank_mask:0xf
	v_fmac_f32_dpp v148, v93, v137 row_shl:14 row_mask:0xf bank_mask:0xf
	v_fmac_f32_dpp v148, v49, v121 row_shr:1 row_mask:0xf bank_mask:0xf
	v_fmac_f32_dpp v148, v93, v121 row_shl:15 row_mask:0xf bank_mask:0xf
	s_waitcnt lgkmcnt(0)
	v_cndmask_b32_e64 v49, v142, v102, s[8:9]
	v_fma_f32 v151, v90, v130, v30
	v_fmac_f32_dpp v151, v90, v134 row_shr:2 row_mask:0xf bank_mask:0xf
	v_fmac_f32_dpp v151, v94, v134 row_shl:14 row_mask:0xf bank_mask:0xf
	v_fmac_f32_dpp v151, v90, v118 row_shr:1 row_mask:0xf bank_mask:0xf
	v_fmac_f32_dpp v151, v94, v118 row_shl:15 row_mask:0xf bank_mask:0xf
	v_fma_f32 v215, v91, v131, v31
	v_fmac_f32_dpp v215, v91, v135 row_shr:2 row_mask:0xf bank_mask:0xf
	v_fmac_f32_dpp v215, v95, v135 row_shl:14 row_mask:0xf bank_mask:0xf
	v_fmac_f32_dpp v215, v91, v119 row_shr:1 row_mask:0xf bank_mask:0xf
	v_fmac_f32_dpp v215, v95, v119 row_shl:15 row_mask:0xf bank_mask:0xf
	v_fma_f32 v150, v92, v132, v32
	v_fmac_f32_dpp v150, v92, v136 row_shr:2 row_mask:0xf bank_mask:0xf
	v_fmac_f32_dpp v150, v96, v136 row_shl:14 row_mask:0xf bank_mask:0xf
	v_fmac_f32_dpp v150, v92, v120 row_shr:1 row_mask:0xf bank_mask:0xf
	v_fmac_f32_dpp v150, v96, v120 row_shl:15 row_mask:0xf bank_mask:0xf
	v_fma_f32 v155, v93, v133, v33
	v_fmac_f32_dpp v155, v93, v137 row_shr:2 row_mask:0xf bank_mask:0xf
	v_fmac_f32_dpp v155, v97, v137 row_shl:14 row_mask:0xf bank_mask:0xf
	v_fmac_f32_dpp v155, v93, v121 row_shr:1 row_mask:0xf bank_mask:0xf
	v_fmac_f32_dpp v155, v97, v121 row_shl:15 row_mask:0xf bank_mask:0xf
	v_fma_f32 v229, v94, v130, v30
	v_fmac_f32_dpp v229, v94, v134 row_shr:2 row_mask:0xf bank_mask:0xf
	v_fmac_f32_dpp v229, v49, v134 row_shl:14 row_mask:0xf bank_mask:0xf
	v_fmac_f32_dpp v229, v94, v118 row_shr:1 row_mask:0xf bank_mask:0xf
	v_fmac_f32_dpp v229, v49, v118 row_shl:15 row_mask:0xf bank_mask:0xf
	v_cndmask_b32_e64 v48, v143, v103, s[8:9]
	v_mov_b32_e32 v134, v229
	v_cndmask_b32_e64 v47, v144, v104, s[8:9]
	v_fma_f32 v130, v95, v131, v31
	v_fmac_f32_dpp v130, v95, v135 row_shr:2 row_mask:0xf bank_mask:0xf
	v_fmac_f32_dpp v130, v48, v135 row_shl:14 row_mask:0xf bank_mask:0xf
	v_fmac_f32_dpp v130, v95, v119 row_shr:1 row_mask:0xf bank_mask:0xf
	v_fmac_f32_dpp v130, v48, v119 row_shl:15 row_mask:0xf bank_mask:0xf
	v_fma_f32 v229, v96, v132, v32
	v_fmac_f32_dpp v229, v96, v136 row_shr:2 row_mask:0xf bank_mask:0xf
	v_fmac_f32_dpp v229, v47, v136 row_shl:14 row_mask:0xf bank_mask:0xf
	v_fmac_f32_dpp v229, v96, v120 row_shr:1 row_mask:0xf bank_mask:0xf
	v_fmac_f32_dpp v229, v47, v120 row_shl:15 row_mask:0xf bank_mask:0xf
	v_cndmask_b32_e64 v46, v145, v105, s[8:9]
	v_fma_f32 v231, v97, v133, v33
	v_fmac_f32_dpp v231, v97, v137 row_shr:2 row_mask:0xf bank_mask:0xf
	v_fmac_f32_dpp v231, v46, v137 row_shl:14 row_mask:0xf bank_mask:0xf
	v_fmac_f32_dpp v231, v97, v121 row_shr:1 row_mask:0xf bank_mask:0xf
	v_fmac_f32_dpp v231, v46, v121 row_shl:15 row_mask:0xf bank_mask:0xf
	v_or_b32_e32 v30, 4, v186
	v_ashrrev_i32_e32 v31, 31, v30
	v_mov_b32_e32 v32, v229
	v_mov_b32_e32 v33, v231
	v_lshlrev_b64 v[30:31], 2, v[30:31]
	v_lshl_add_u64 v[46:47], s[20:21], 0, v[30:31]
	v_lshl_add_u64 v[30:31], s[22:23], 0, v[30:31]
	s_nop 0
	v_mov_b32_e32 v106, 0
	s_and_b64 vcc, exec, s[10:11]
	v_mov_b32_e32 v118, 0
	v_mov_b32_e32 v119, 0
	v_mov_b32_e32 v120, 0
	v_mov_b32_e32 v121, 0
	v_mov_b32_e32 v126, 0
	v_mov_b32_e32 v127, 0
	v_mov_b32_e32 v128, 0
	v_mov_b32_e32 v129, 0
	s_cbranch_vccnz .LBB0_1190
	v_add_u32_e32 v31, 0xfffff810, v227
	v_add_u32_e32 v30, 0xfffffc10, v227
	ds_read_b128 v[118:121], v31
	ds_read_b128 v[126:129], v30
; #define PG8_LAS __attribute__((address_space(3)))
;     __device__ __forceinline__ void operator()(f32x4 (&acc)[2][2][4][2], const Unit& u, int ui, int wr, int wc, int fr_, int fq_) const {
;     ...
;             for (int m = 0; m < 4; ++m) { const float r = rtab[ui * 256 + ai * HALF + wr * 64 + m * 16 + fr];
; #pragma unroll
;                 for (int bj = 0; bj < 2; ++bj)
; #pragma unroll
;                     for (int n = 0; n < 2; ++n) acc[ai][bj][m][n] = acc[ai][bj][m][n] * r; }
;     ...
;                 for (int ai = 0; ai < 2; ++ai) { const int kb = 2 * ai + wr;
;                     f32x4 c62 = (f32x4){0.f, 0.f, 0.f, 0.f}, c63 = c62;
;                     if (kb > 0) { c62 = *(const PG8_LAS f32x4*)(exch + (((kb - 1) * 2 + 0) * 256 + bj * HALF + 32 * wc + 8 * fq + 4 * n)); c63 = *(const PG8_LAS f32x4*)(exch + (((kb - 1) * 2 + 1) * 256 + bj * HALF + 32 * wc + 8 * fq + 4 * n)); }
; #pragma unroll
;                     for (int m = 3; m >= 0; --m) { f32x4 cur = acc[ai][bj][m][n], res;
; #pragma unroll
;                         for (int j = 0; j < 4; ++j) { const float c = cur[j]; const float pv = (m > 0) ? acc[ai][bj][m > 0 ? m - 1 : 0][n][j] : (fr == 15 ? c63[j] : c62[j]); float t1, t2;
;                             asm volatile("s_nop 1\n\tv_mov_b32_dpp %0, %3 row_ror:1 row_mask:0xf bank_mask:0xf\n\tv_mov_b32_dpp %1, %3 row_ror:2 row_mask:0xf bank_mask:0xf\n\t"
;                                          "v_mov_b32_dpp %0, %2 row_shr:1 row_mask:0xf bank_mask:0xf\n\tv_mov_b32_dpp %1, %2 row_shr:2 row_mask:0xf bank_mask:0xf"
;                                          : "=&v"(t1), "=&v"(t2) : "v"(c), "v"(pv));
;                             res[j] = bb[j] + w0[j] * t2 + w1[j] * t1 + w2[j] * c; }
;                         asm volatile("" : "+v"(res[0]), "+v"(res[1]), "+v"(res[2]), "+v"(res[3]));
;                         acc[ai][bj][m][n] = res; } }
.LBB0_1190:
	v_mov_b32_e32 v30, v194
	v_mov_b32_e32 v31, v194
	v_mov_b32_e32 v197, v196
	v_pk_mul_f32 v[30:31], v[80:81], v[30:31]
	v_pk_mul_f32 v[76:77], v[76:77], v[196:197] op_sel_hi:[1,0]
	v_pk_mul_f32 v[74:75], v[74:75], v[196:197]
	v_mov_b32_e32 v195, v194
	v_pk_mul_f32 v[78:79], v[78:79], v[194:195]
	s_waitcnt vmcnt(0)
	v_fma_f32 v133, v110, v244, v248
	v_fmac_f32_dpp v133, v110, v234 row_shr:2 row_mask:0xf bank_mask:0xf
	v_fmac_f32_dpp v133, v74, v234 row_shl:14 row_mask:0xf bank_mask:0xf
	v_fmac_f32_dpp v133, v110, v240 row_shr:1 row_mask:0xf bank_mask:0xf
	v_fmac_f32_dpp v133, v74, v240 row_shl:15 row_mask:0xf bank_mask:0xf
	v_fma_f32 v131, v111, v245, v249
	v_fmac_f32_dpp v131, v111, v235 row_shr:2 row_mask:0xf bank_mask:0xf
	v_fmac_f32_dpp v131, v75, v235 row_shl:14 row_mask:0xf bank_mask:0xf
	v_fmac_f32_dpp v131, v111, v241 row_shr:1 row_mask:0xf bank_mask:0xf
	v_fmac_f32_dpp v131, v75, v241 row_shl:15 row_mask:0xf bank_mask:0xf
	v_fma_f32 v132, v112, v246, v250
	v_fmac_f32_dpp v132, v112, v236 row_shr:2 row_mask:0xf bank_mask:0xf
	v_fmac_f32_dpp v132, v76, v236 row_shl:14 row_mask:0xf bank_mask:0xf
	v_fmac_f32_dpp v132, v112, v242 row_shr:1 row_mask:0xf bank_mask:0xf
	v_fmac_f32_dpp v132, v76, v242 row_shl:15 row_mask:0xf bank_mask:0xf
	v_fma_f32 v135, v113, v247, v251
	v_fmac_f32_dpp v135, v113, v237 row_shr:2 row_mask:0xf bank_mask:0xf
	v_fmac_f32_dpp v135, v77, v237 row_shl:14 row_mask:0xf bank_mask:0xf
	v_fmac_f32_dpp v135, v113, v243 row_shr:1 row_mask:0xf bank_mask:0xf
	v_fmac_f32_dpp v135, v77, v243 row_shl:15 row_mask:0xf bank_mask:0xf
	s_and_b64 vcc, exec, s[12:13]
	v_fma_f32 v142, v74, v244, v248
	v_fmac_f32_dpp v142, v74, v234 row_shr:2 row_mask:0xf bank_mask:0xf
	v_fmac_f32_dpp v142, v78, v234 row_shl:14 row_mask:0xf bank_mask:0xf
	v_fmac_f32_dpp v142, v74, v240 row_shr:1 row_mask:0xf bank_mask:0xf
	v_fmac_f32_dpp v142, v78, v240 row_shl:15 row_mask:0xf bank_mask:0xf
	v_mov_b32_e32 v107, 0
	v_fma_f32 v136, v75, v245, v249
	v_fmac_f32_dpp v136, v75, v235 row_shr:2 row_mask:0xf bank_mask:0xf
	v_fmac_f32_dpp v136, v79, v235 row_shl:14 row_mask:0xf bank_mask:0xf
	v_fmac_f32_dpp v136, v75, v241 row_shr:1 row_mask:0xf bank_mask:0xf
	v_fmac_f32_dpp v136, v79, v241 row_shl:15 row_mask:0xf bank_mask:0xf
	v_mov_b32_e32 v108, 0
	v_fma_f32 v137, v76, v246, v250
	v_fmac_f32_dpp v137, v76, v236 row_shr:2 row_mask:0xf bank_mask:0xf
	v_fmac_f32_dpp v137, v30, v236 row_shl:14 row_mask:0xf bank_mask:0xf
	v_fmac_f32_dpp v137, v76, v242 row_shr:1 row_mask:0xf bank_mask:0xf
	v_fmac_f32_dpp v137, v30, v242 row_shl:15 row_mask:0xf bank_mask:0xf
	v_fma_f32 v143, v77, v247, v251
	v_fmac_f32_dpp v143, v77, v237 row_shr:2 row_mask:0xf bank_mask:0xf
	v_fmac_f32_dpp v143, v31, v237 row_shl:14 row_mask:0xf bank_mask:0xf
	v_fmac_f32_dpp v143, v77, v243 row_shr:1 row_mask:0xf bank_mask:0xf
	v_fmac_f32_dpp v143, v31, v243 row_shl:15 row_mask:0xf bank_mask:0xf
	v_mov_b32_e32 v109, 0
	v_fma_f32 v225, v78, v244, v248
	v_fmac_f32_dpp v225, v78, v234 row_shr:2 row_mask:0xf bank_mask:0xf
	v_fmac_f32_dpp v225, v122, v234 row_shl:14 row_mask:0xf bank_mask:0xf
	v_fmac_f32_dpp v225, v78, v240 row_shr:1 row_mask:0xf bank_mask:0xf
	v_fmac_f32_dpp v225, v122, v240 row_shl:15 row_mask:0xf bank_mask:0xf
	v_fma_f32 v144, v79, v245, v249
	v_fmac_f32_dpp v144, v79, v235 row_shr:2 row_mask:0xf bank_mask:0xf
	v_fmac_f32_dpp v144, v123, v235 row_shl:14 row_mask:0xf bank_mask:0xf
	v_fmac_f32_dpp v144, v79, v241 row_shr:1 row_mask:0xf bank_mask:0xf
	v_fmac_f32_dpp v144, v123, v241 row_shl:15 row_mask:0xf bank_mask:0xf
	v_fma_f32 v145, v30, v246, v250
	v_fmac_f32_dpp v145, v30, v236 row_shr:2 row_mask:0xf bank_mask:0xf
	v_fmac_f32_dpp v145, v124, v236 row_shl:14 row_mask:0xf bank_mask:0xf
	v_fmac_f32_dpp v145, v30, v242 row_shr:1 row_mask:0xf bank_mask:0xf
	v_fmac_f32_dpp v145, v124, v242 row_shl:15 row_mask:0xf bank_mask:0xf
	s_waitcnt lgkmcnt(0)
	v_cndmask_b32_e64 v75, v118, v126, s[8:9]
	v_fma_f32 v226, v31, v247, v251
	v_fmac_f32_dpp v226, v31, v237 row_shr:2 row_mask:0xf bank_mask:0xf
	v_fmac_f32_dpp v226, v125, v237 row_shl:14 row_mask:0xf bank_mask:0xf
	v_fmac_f32_dpp v226, v31, v243 row_shr:1 row_mask:0xf bank_mask:0xf
	v_fmac_f32_dpp v226, v125, v243 row_shl:15 row_mask:0xf bank_mask:0xf
	v_cndmask_b32_e64 v74, v119, v127, s[8:9]
	v_fma_f32 v126, v122, v244, v248
	v_fmac_f32_dpp v126, v122, v234 row_shr:2 row_mask:0xf bank_mask:0xf
	v_fmac_f32_dpp v126, v75, v234 row_shl:14 row_mask:0xf bank_mask:0xf
	v_fmac_f32_dpp v126, v122, v240 row_shr:1 row_mask:0xf bank_mask:0xf
	v_fmac_f32_dpp v126, v75, v240 row_shl:15 row_mask:0xf bank_mask:0xf
	v_cndmask_b32_e64 v31, v120, v128, s[8:9]
	v_fma_f32 v122, v123, v245, v249
	v_fmac_f32_dpp v122, v123, v235 row_shr:2 row_mask:0xf bank_mask:0xf
	v_fmac_f32_dpp v122, v74, v235 row_shl:14 row_mask:0xf bank_mask:0xf
	v_fmac_f32_dpp v122, v123, v241 row_shr:1 row_mask:0xf bank_mask:0xf
	v_fmac_f32_dpp v122, v74, v241 row_shl:15 row_mask:0xf bank_mask:0xf
	v_cndmask_b32_e64 v30, v121, v129, s[8:9]
	v_fma_f32 v123, v124, v246, v250
	v_fmac_f32_dpp v123, v124, v236 row_shr:2 row_mask:0xf bank_mask:0xf
	v_fmac_f32_dpp v123, v31, v236 row_shl:14 row_mask:0xf bank_mask:0xf
	v_fmac_f32_dpp v123, v124, v242 row_shr:1 row_mask:0xf bank_mask:0xf
	v_fmac_f32_dpp v123, v31, v242 row_shl:15 row_mask:0xf bank_mask:0xf
	v_mov_b32_e32 v75, 0
	v_fma_f32 v124, v125, v247, v251
	v_fmac_f32_dpp v124, v125, v237 row_shr:2 row_mask:0xf bank_mask:0xf
	v_fmac_f32_dpp v124, v30, v237 row_shl:14 row_mask:0xf bank_mask:0xf
	v_fmac_f32_dpp v124, v125, v243 row_shr:1 row_mask:0xf bank_mask:0xf
	v_fmac_f32_dpp v124, v30, v243 row_shl:15 row_mask:0xf bank_mask:0xf
	v_mov_b32_e32 v74, 0
	v_mov_b32_e32 v76, 0
	v_mov_b32_e32 v77, 0
	s_cbranch_vccnz .LBB0_1192
	ds_read_b128 v[106:109], v227 offset:2064
	ds_read_b128 v[74:77], v227 offset:3088
; #define PG8_LAS __attribute__((address_space(3)))
;     __device__ __forceinline__ void operator()(f32x4 (&acc)[2][2][4][2], const Unit& u, int ui, int wr, int wc, int fr_, int fq_) const {
;     ...
;             for (int m = 0; m < 4; ++m) { const float r = rtab[ui * 256 + ai * HALF + wr * 64 + m * 16 + fr];
; #pragma unroll
;                 for (int bj = 0; bj < 2; ++bj)
; #pragma unroll
;                     for (int n = 0; n < 2; ++n) acc[ai][bj][m][n] = acc[ai][bj][m][n] * r; }
;     ...
;             for (int n = 0; n < 2; ++n) { const int ch = bj * 2816 + fbase + 4 * n;
;                 const f32x4 w0 = *(const f32x4*)(cw + ch), w1 = *(const f32x4*)(cw + 5632 + ch), w2 = *(const f32x4*)(cw + 2 * 5632 + ch), bb = *(const f32x4*)(cb + ch);
; #pragma unroll
;                 for (int ai = 0; ai < 2; ++ai) { const int kb = 2 * ai + wr;
;                     f32x4 c62 = (f32x4){0.f, 0.f, 0.f, 0.f}, c63 = c62;
;                     if (kb > 0) { c62 = *(const PG8_LAS f32x4*)(exch + (((kb - 1) * 2 + 0) * 256 + bj * HALF + 32 * wc + 8 * fq + 4 * n)); c63 = *(const PG8_LAS f32x4*)(exch + (((kb - 1) * 2 + 1) * 256 + bj * HALF + 32 * wc + 8 * fq + 4 * n)); }
; #pragma unroll
;                     for (int m = 3; m >= 0; --m) { f32x4 cur = acc[ai][bj][m][n], res;
; #pragma unroll
;                         for (int j = 0; j < 4; ++j) { const float c = cur[j]; const float pv = (m > 0) ? acc[ai][bj][m > 0 ? m - 1 : 0][n][j] : (fr == 15 ? c63[j] : c62[j]); float t1, t2;
;                             asm volatile("s_nop 1\n\tv_mov_b32_dpp %0, %3 row_ror:1 row_mask:0xf bank_mask:0xf\n\tv_mov_b32_dpp %1, %3 row_ror:2 row_mask:0xf bank_mask:0xf\n\t"
;                                          "v_mov_b32_dpp %0, %2 row_shr:1 row_mask:0xf bank_mask:0xf\n\tv_mov_b32_dpp %1, %2 row_shr:2 row_mask:0xf bank_mask:0xf"
;                                          : "=&v"(t1), "=&v"(t2) : "v"(c), "v"(pv));
;                             res[j] = bb[j] + w0[j] * t2 + w1[j] * t1 + w2[j] * c; }
;                         asm volatile("" : "+v"(res[0]), "+v"(res[1]), "+v"(res[2]), "+v"(res[3]));
;                         acc[ai][bj][m][n] = res; } }
.LBB0_1192:
	v_mov_b32_e32 v30, v192
	v_mov_b32_e32 v31, v192
	v_pk_mul_f32 v[30:31], v[68:69], v[30:31]
	v_mov_b32_e32 v189, v188
	v_pk_mul_f32 v[64:65], v[64:65], v[190:191] op_sel_hi:[1,0]
	v_mov_b32_e32 v68, v188
	v_mov_b32_e32 v69, v188
	v_pk_mul_f32 v[56:57], v[56:57], v[68:69]
	v_pk_mul_f32 v[54:55], v[54:55], v[188:189]
	v_mov_b32_e32 v191, v190
	v_pk_mul_f32 v[62:63], v[62:63], v[190:191]
	v_fma_f32 v112, v114, v244, v248
	v_fmac_f32_dpp v112, v114, v234 row_shr:2 row_mask:0xf bank_mask:0xf
	v_fmac_f32_dpp v112, v54, v234 row_shl:14 row_mask:0xf bank_mask:0xf
	v_fmac_f32_dpp v112, v114, v240 row_shr:1 row_mask:0xf bank_mask:0xf
	v_fmac_f32_dpp v112, v54, v240 row_shl:15 row_mask:0xf bank_mask:0xf
	v_fma_f32 v110, v115, v245, v249
	v_fmac_f32_dpp v110, v115, v235 row_shr:2 row_mask:0xf bank_mask:0xf
	v_fmac_f32_dpp v110, v55, v235 row_shl:14 row_mask:0xf bank_mask:0xf
	v_fmac_f32_dpp v110, v115, v241 row_shr:1 row_mask:0xf bank_mask:0xf
	v_fmac_f32_dpp v110, v55, v241 row_shl:15 row_mask:0xf bank_mask:0xf
	v_fma_f32 v111, v116, v246, v250
	v_fmac_f32_dpp v111, v116, v236 row_shr:2 row_mask:0xf bank_mask:0xf
	v_fmac_f32_dpp v111, v56, v236 row_shl:14 row_mask:0xf bank_mask:0xf
	v_fmac_f32_dpp v111, v116, v242 row_shr:1 row_mask:0xf bank_mask:0xf
	v_fmac_f32_dpp v111, v56, v242 row_shl:15 row_mask:0xf bank_mask:0xf
	v_fma_f32 v113, v117, v247, v251
	v_fmac_f32_dpp v113, v117, v237 row_shr:2 row_mask:0xf bank_mask:0xf
	v_fmac_f32_dpp v113, v57, v237 row_shl:14 row_mask:0xf bank_mask:0xf
	v_fmac_f32_dpp v113, v117, v243 row_shr:1 row_mask:0xf bank_mask:0xf
	v_fmac_f32_dpp v113, v57, v243 row_shl:15 row_mask:0xf bank_mask:0xf
	v_mov_b32_e32 v193, v192
	v_fma_f32 v116, v54, v244, v248
	v_fmac_f32_dpp v116, v54, v234 row_shr:2 row_mask:0xf bank_mask:0xf
	v_fmac_f32_dpp v116, v62, v234 row_shl:14 row_mask:0xf bank_mask:0xf
	v_fmac_f32_dpp v116, v54, v240 row_shr:1 row_mask:0xf bank_mask:0xf
	v_fmac_f32_dpp v116, v62, v240 row_shl:15 row_mask:0xf bank_mask:0xf
	v_pk_mul_f32 v[66:67], v[66:67], v[192:193]
	v_fma_f32 v114, v55, v245, v249
	v_fmac_f32_dpp v114, v55, v235 row_shr:2 row_mask:0xf bank_mask:0xf
	v_fmac_f32_dpp v114, v63, v235 row_shl:14 row_mask:0xf bank_mask:0xf
	v_fmac_f32_dpp v114, v55, v241 row_shr:1 row_mask:0xf bank_mask:0xf
	v_fmac_f32_dpp v114, v63, v241 row_shl:15 row_mask:0xf bank_mask:0xf
	s_movk_i32 s0, 0x2000
	v_fma_f32 v115, v56, v246, v250
	v_fmac_f32_dpp v115, v56, v236 row_shr:2 row_mask:0xf bank_mask:0xf
	v_fmac_f32_dpp v115, v64, v236 row_shl:14 row_mask:0xf bank_mask:0xf
	v_fmac_f32_dpp v115, v56, v242 row_shr:1 row_mask:0xf bank_mask:0xf
	v_fmac_f32_dpp v115, v64, v242 row_shl:15 row_mask:0xf bank_mask:0xf
	v_fma_f32 v117, v57, v247, v251
	v_fmac_f32_dpp v117, v57, v237 row_shr:2 row_mask:0xf bank_mask:0xf
	v_fmac_f32_dpp v117, v65, v237 row_shl:14 row_mask:0xf bank_mask:0xf
	v_fmac_f32_dpp v117, v57, v243 row_shr:1 row_mask:0xf bank_mask:0xf
	v_fmac_f32_dpp v117, v65, v243 row_shl:15 row_mask:0xf bank_mask:0xf
	s_waitcnt lgkmcnt(0)
	v_cndmask_b32_e64 v57, v106, v74, s[8:9]
	v_fma_f32 v120, v62, v244, v248
	v_fmac_f32_dpp v120, v62, v234 row_shr:2 row_mask:0xf bank_mask:0xf
	v_fmac_f32_dpp v120, v66, v234 row_shl:14 row_mask:0xf bank_mask:0xf
	v_fmac_f32_dpp v120, v62, v240 row_shr:1 row_mask:0xf bank_mask:0xf
	v_fmac_f32_dpp v120, v66, v240 row_shl:15 row_mask:0xf bank_mask:0xf
	v_fma_f32 v118, v63, v245, v249
	v_fmac_f32_dpp v118, v63, v235 row_shr:2 row_mask:0xf bank_mask:0xf
	v_fmac_f32_dpp v118, v67, v235 row_shl:14 row_mask:0xf bank_mask:0xf
	v_fmac_f32_dpp v118, v63, v241 row_shr:1 row_mask:0xf bank_mask:0xf
	v_fmac_f32_dpp v118, v67, v241 row_shl:15 row_mask:0xf bank_mask:0xf
	v_fma_f32 v119, v64, v246, v250
	v_fmac_f32_dpp v119, v64, v236 row_shr:2 row_mask:0xf bank_mask:0xf
	v_fmac_f32_dpp v119, v30, v236 row_shl:14 row_mask:0xf bank_mask:0xf
	v_fmac_f32_dpp v119, v64, v242 row_shr:1 row_mask:0xf bank_mask:0xf
	v_fmac_f32_dpp v119, v30, v242 row_shl:15 row_mask:0xf bank_mask:0xf
	v_fma_f32 v121, v65, v247, v251
	v_fmac_f32_dpp v121, v65, v237 row_shr:2 row_mask:0xf bank_mask:0xf
	v_fmac_f32_dpp v121, v31, v237 row_shl:14 row_mask:0xf bank_mask:0xf
	v_fmac_f32_dpp v121, v65, v243 row_shr:1 row_mask:0xf bank_mask:0xf
	v_fmac_f32_dpp v121, v31, v243 row_shl:15 row_mask:0xf bank_mask:0xf
	v_cndmask_b32_e64 v56, v107, v75, s[8:9]
	v_fma_f32 v106, v66, v244, v248
	v_fmac_f32_dpp v106, v66, v234 row_shr:2 row_mask:0xf bank_mask:0xf
	v_fmac_f32_dpp v106, v57, v234 row_shl:14 row_mask:0xf bank_mask:0xf
	v_fmac_f32_dpp v106, v66, v240 row_shr:1 row_mask:0xf bank_mask:0xf
	v_fmac_f32_dpp v106, v57, v240 row_shl:15 row_mask:0xf bank_mask:0xf
	v_cndmask_b32_e64 v55, v108, v76, s[8:9]
	v_fma_f32 v102, v67, v245, v249
	v_fmac_f32_dpp v102, v67, v235 row_shr:2 row_mask:0xf bank_mask:0xf
	v_fmac_f32_dpp v102, v56, v235 row_shl:14 row_mask:0xf bank_mask:0xf
	v_fmac_f32_dpp v102, v67, v241 row_shr:1 row_mask:0xf bank_mask:0xf
	v_fmac_f32_dpp v102, v56, v241 row_shl:15 row_mask:0xf bank_mask:0xf
	v_fma_f32 v48, v30, v246, v250
	v_fmac_f32_dpp v48, v30, v236 row_shr:2 row_mask:0xf bank_mask:0xf
	v_fmac_f32_dpp v48, v55, v236 row_shl:14 row_mask:0xf bank_mask:0xf
	v_fmac_f32_dpp v48, v30, v242 row_shr:1 row_mask:0xf bank_mask:0xf
	v_fmac_f32_dpp v48, v55, v242 row_shl:15 row_mask:0xf bank_mask:0xf
	v_cndmask_b32_e64 v54, v109, v77, s[8:9]
	v_fma_f32 v49, v31, v247, v251
	v_fmac_f32_dpp v49, v31, v237 row_shr:2 row_mask:0xf bank_mask:0xf
	v_fmac_f32_dpp v49, v54, v237 row_shl:14 row_mask:0xf bank_mask:0xf
	v_fmac_f32_dpp v49, v31, v243 row_shr:1 row_mask:0xf bank_mask:0xf
	v_fmac_f32_dpp v49, v54, v243 row_shl:15 row_mask:0xf bank_mask:0xf
	v_add_co_u32_e32 v30, vcc, s0, v204
	s_nop 0
	v_addc_co_u32_e32 v31, vcc, 0, v205, vcc
	v_add_co_u32_e32 v46, vcc, s0, v202
	s_nop 0
	v_addc_co_u32_e32 v47, vcc, 0, v203, vcc
	v_add_co_u32_e32 v54, vcc, 0x2000, v200
	global_load_dwordx4 v[62:65], v[30:31], off offset:3072
	global_load_dwordx4 v[66:69], v[46:47], off offset:3072
	global_load_dwordx4 v[234:237], v[30:31], off offset:3088
	global_load_dwordx4 v[240:243], v[46:47], off offset:3088
	v_addc_co_u32_e32 v55, vcc, 0, v201, vcc
	global_load_dwordx4 v[74:77], v[54:55], off offset:3072
	global_load_dwordx4 v[244:247], v[54:55], off offset:3088
	v_add_co_u32_e32 v54, vcc, 0x2000, v198
	v_mov_b32_e32 v78, 0
	s_nop 0
	v_addc_co_u32_e32 v55, vcc, 0, v199, vcc
	global_load_dwordx4 v[248:251], v[54:55], off offset:3088
	global_load_dwordx4 v[54:57], v[54:55], off offset:3072
	s_and_b64 vcc, exec, s[10:11]
	v_mov_b32_e32 v90, 0
	v_mov_b32_e32 v91, 0
	v_mov_b32_e32 v92, 0
	v_mov_b32_e32 v93, 0
	v_mov_b32_e32 v94, 0
	v_mov_b32_e32 v95, 0
	v_mov_b32_e32 v96, 0
	v_mov_b32_e32 v97, 0
	s_cbranch_vccnz .LBB0_1194
	v_add_u32_e32 v80, s43, v228
	v_add_u32_e32 v79, s30, v228
	ds_read_b128 v[90:93], v80
	ds_read_b128 v[94:97], v79
; #define PG8_LAS __attribute__((address_space(3)))
;     __device__ __forceinline__ void operator()(f32x4 (&acc)[2][2][4][2], const Unit& u, int ui, int wr, int wc, int fr_, int fq_) const {
;     ...
;             for (int m = 0; m < 4; ++m) { const float r = rtab[ui * 256 + ai * HALF + wr * 64 + m * 16 + fr];
; #pragma unroll
;                 for (int bj = 0; bj < 2; ++bj)
; #pragma unroll
;                     for (int n = 0; n < 2; ++n) acc[ai][bj][m][n] = acc[ai][bj][m][n] * r; }
;     ...
;                 for (int ai = 0; ai < 2; ++ai) { const int kb = 2 * ai + wr;
;                     f32x4 c62 = (f32x4){0.f, 0.f, 0.f, 0.f}, c63 = c62;
;                     if (kb > 0) { c62 = *(const PG8_LAS f32x4*)(exch + (((kb - 1) * 2 + 0) * 256 + bj * HALF + 32 * wc + 8 * fq + 4 * n)); c63 = *(const PG8_LAS f32x4*)(exch + (((kb - 1) * 2 + 1) * 256 + bj * HALF + 32 * wc + 8 * fq + 4 * n)); }
; #pragma unroll
;                     for (int m = 3; m >= 0; --m) { f32x4 cur = acc[ai][bj][m][n], res;
; #pragma unroll
;                         for (int j = 0; j < 4; ++j) { const float c = cur[j]; const float pv = (m > 0) ? acc[ai][bj][m > 0 ? m - 1 : 0][n][j] : (fr == 15 ? c63[j] : c62[j]); float t1, t2;
;                             asm volatile("s_nop 1\n\tv_mov_b32_dpp %0, %3 row_ror:1 row_mask:0xf bank_mask:0xf\n\tv_mov_b32_dpp %1, %3 row_ror:2 row_mask:0xf bank_mask:0xf\n\t"
;                                          "v_mov_b32_dpp %0, %2 row_shr:1 row_mask:0xf bank_mask:0xf\n\tv_mov_b32_dpp %1, %2 row_shr:2 row_mask:0xf bank_mask:0xf"
;                                          : "=&v"(t1), "=&v"(t2) : "v"(c), "v"(pv));
;                             res[j] = bb[j] + w0[j] * t2 + w1[j] * t1 + w2[j] * c; }
;                         asm volatile("" : "+v"(res[0]), "+v"(res[1]), "+v"(res[2]), "+v"(res[3]));
;                         acc[ai][bj][m][n] = res; } }
.LBB0_1194:
	v_pk_mul_f32 v[44:45], v[44:45], v[194:195] op_sel_hi:[1,0]
	v_pk_mul_f32 v[40:41], v[40:41], v[196:197] op_sel_hi:[1,0]
	v_pk_mul_f32 v[38:39], v[38:39], v[196:197]
	v_pk_mul_f32 v[42:43], v[42:43], v[194:195]
	s_and_b64 vcc, exec, s[12:13]
	s_waitcnt vmcnt(0)
	v_fma_f32 v104, v98, v74, v54
	v_fmac_f32_dpp v104, v98, v62 row_shr:2 row_mask:0xf bank_mask:0xf
	v_fmac_f32_dpp v104, v38, v62 row_shl:14 row_mask:0xf bank_mask:0xf
	v_fmac_f32_dpp v104, v98, v66 row_shr:1 row_mask:0xf bank_mask:0xf
	v_fmac_f32_dpp v104, v38, v66 row_shl:15 row_mask:0xf bank_mask:0xf
	v_fma_f32 v103, v99, v75, v55
	v_fmac_f32_dpp v103, v99, v63 row_shr:2 row_mask:0xf bank_mask:0xf
	v_fmac_f32_dpp v103, v39, v63 row_shl:14 row_mask:0xf bank_mask:0xf
	v_fmac_f32_dpp v103, v99, v67 row_shr:1 row_mask:0xf bank_mask:0xf
	v_fmac_f32_dpp v103, v39, v67 row_shl:15 row_mask:0xf bank_mask:0xf
	v_fma_f32 v98, v100, v76, v56
	v_fmac_f32_dpp v98, v100, v64 row_shr:2 row_mask:0xf bank_mask:0xf
	v_fmac_f32_dpp v98, v40, v64 row_shl:14 row_mask:0xf bank_mask:0xf
	v_fmac_f32_dpp v98, v100, v68 row_shr:1 row_mask:0xf bank_mask:0xf
	v_fmac_f32_dpp v98, v40, v68 row_shl:15 row_mask:0xf bank_mask:0xf
	v_fma_f32 v99, v101, v77, v57
	v_fmac_f32_dpp v99, v101, v65 row_shr:2 row_mask:0xf bank_mask:0xf
	v_fmac_f32_dpp v99, v41, v65 row_shl:14 row_mask:0xf bank_mask:0xf
	v_fmac_f32_dpp v99, v101, v69 row_shr:1 row_mask:0xf bank_mask:0xf
	v_fmac_f32_dpp v99, v41, v69 row_shl:15 row_mask:0xf bank_mask:0xf
	v_mov_b32_e32 v81, 0
	v_fma_f32 v107, v38, v74, v54
	v_fmac_f32_dpp v107, v38, v62 row_shr:2 row_mask:0xf bank_mask:0xf
	v_fmac_f32_dpp v107, v42, v62 row_shl:14 row_mask:0xf bank_mask:0xf
	v_fmac_f32_dpp v107, v38, v66 row_shr:1 row_mask:0xf bank_mask:0xf
	v_fmac_f32_dpp v107, v42, v66 row_shl:15 row_mask:0xf bank_mask:0xf
	v_mov_b32_e32 v80, 0
	v_fma_f32 v105, v39, v75, v55
	v_fmac_f32_dpp v105, v39, v63 row_shr:2 row_mask:0xf bank_mask:0xf
	v_fmac_f32_dpp v105, v43, v63 row_shl:14 row_mask:0xf bank_mask:0xf
	v_fmac_f32_dpp v105, v39, v67 row_shr:1 row_mask:0xf bank_mask:0xf
	v_fmac_f32_dpp v105, v43, v67 row_shl:15 row_mask:0xf bank_mask:0xf
	v_mov_b32_e32 v79, 0
	v_fma_f32 v100, v40, v76, v56
	v_fmac_f32_dpp v100, v40, v64 row_shr:2 row_mask:0xf bank_mask:0xf
	v_fmac_f32_dpp v100, v44, v64 row_shl:14 row_mask:0xf bank_mask:0xf
	v_fmac_f32_dpp v100, v40, v68 row_shr:1 row_mask:0xf bank_mask:0xf
	v_fmac_f32_dpp v100, v44, v68 row_shl:15 row_mask:0xf bank_mask:0xf
	v_fma_f32 v101, v41, v77, v57
	v_fmac_f32_dpp v101, v41, v65 row_shr:2 row_mask:0xf bank_mask:0xf
	v_fmac_f32_dpp v101, v45, v65 row_shl:14 row_mask:0xf bank_mask:0xf
	v_fmac_f32_dpp v101, v41, v69 row_shr:1 row_mask:0xf bank_mask:0xf
	v_fmac_f32_dpp v101, v45, v69 row_shl:15 row_mask:0xf bank_mask:0xf
	s_waitcnt lgkmcnt(0)
	v_cndmask_b32_e64 v41, v90, v94, s[8:9]
	v_fma_f32 v127, v42, v74, v54
	v_fmac_f32_dpp v127, v42, v62 row_shr:2 row_mask:0xf bank_mask:0xf
	v_fmac_f32_dpp v127, v86, v62 row_shl:14 row_mask:0xf bank_mask:0xf
	v_fmac_f32_dpp v127, v42, v66 row_shr:1 row_mask:0xf bank_mask:0xf
	v_fmac_f32_dpp v127, v86, v66 row_shl:15 row_mask:0xf bank_mask:0xf
	v_fma_f32 v125, v43, v75, v55
	v_fmac_f32_dpp v125, v43, v63 row_shr:2 row_mask:0xf bank_mask:0xf
	v_fmac_f32_dpp v125, v87, v63 row_shl:14 row_mask:0xf bank_mask:0xf
	v_fmac_f32_dpp v125, v43, v67 row_shr:1 row_mask:0xf bank_mask:0xf
	v_fmac_f32_dpp v125, v87, v67 row_shl:15 row_mask:0xf bank_mask:0xf
	v_fma_f32 v108, v44, v76, v56
	v_fmac_f32_dpp v108, v44, v64 row_shr:2 row_mask:0xf bank_mask:0xf
	v_fmac_f32_dpp v108, v88, v64 row_shl:14 row_mask:0xf bank_mask:0xf
	v_fmac_f32_dpp v108, v44, v68 row_shr:1 row_mask:0xf bank_mask:0xf
	v_fmac_f32_dpp v108, v88, v68 row_shl:15 row_mask:0xf bank_mask:0xf
	v_fma_f32 v109, v45, v77, v57
	v_fmac_f32_dpp v109, v45, v65 row_shr:2 row_mask:0xf bank_mask:0xf
	v_fmac_f32_dpp v109, v89, v65 row_shl:14 row_mask:0xf bank_mask:0xf
	v_fmac_f32_dpp v109, v45, v69 row_shr:1 row_mask:0xf bank_mask:0xf
	v_fmac_f32_dpp v109, v89, v69 row_shl:15 row_mask:0xf bank_mask:0xf
	v_cndmask_b32_e64 v38, v93, v97, s[8:9]
	v_cndmask_b32_e64 v39, v92, v96, s[8:9]
	v_fma_f32 v97, v86, v74, v54
	v_fmac_f32_dpp v97, v86, v62 row_shr:2 row_mask:0xf bank_mask:0xf
	v_fmac_f32_dpp v97, v41, v62 row_shl:14 row_mask:0xf bank_mask:0xf
	v_fmac_f32_dpp v97, v86, v66 row_shr:1 row_mask:0xf bank_mask:0xf
	v_fmac_f32_dpp v97, v41, v66 row_shl:15 row_mask:0xf bank_mask:0xf
	v_cndmask_b32_e64 v40, v91, v95, s[8:9]
	v_fma_f32 v96, v87, v75, v55
	v_fmac_f32_dpp v96, v87, v63 row_shr:2 row_mask:0xf bank_mask:0xf
	v_fmac_f32_dpp v96, v40, v63 row_shl:14 row_mask:0xf bank_mask:0xf
	v_fmac_f32_dpp v96, v87, v67 row_shr:1 row_mask:0xf bank_mask:0xf
	v_fmac_f32_dpp v96, v40, v67 row_shl:15 row_mask:0xf bank_mask:0xf
	v_fma_f32 v95, v88, v76, v56
	v_fmac_f32_dpp v95, v88, v64 row_shr:2 row_mask:0xf bank_mask:0xf
	v_fmac_f32_dpp v95, v39, v64 row_shl:14 row_mask:0xf bank_mask:0xf
	v_fmac_f32_dpp v95, v88, v68 row_shr:1 row_mask:0xf bank_mask:0xf
	v_fmac_f32_dpp v95, v39, v68 row_shl:15 row_mask:0xf bank_mask:0xf
	v_fma_f32 v94, v89, v77, v57
	v_fmac_f32_dpp v94, v89, v65 row_shr:2 row_mask:0xf bank_mask:0xf
	v_fmac_f32_dpp v94, v38, v65 row_shl:14 row_mask:0xf bank_mask:0xf
	v_fmac_f32_dpp v94, v89, v69 row_shr:1 row_mask:0xf bank_mask:0xf
	v_fmac_f32_dpp v94, v38, v69 row_shl:15 row_mask:0xf bank_mask:0xf
	v_mov_b32_e32 v38, 0
	v_mov_b32_e32 v39, 0
	v_mov_b32_e32 v40, 0
	v_mov_b32_e32 v41, 0
	s_cbranch_vccnz .LBB0_1196
	ds_read_b128 v[78:81], v227 offset:2560
	ds_read_b128 v[38:41], v227 offset:3584
; #define PG8_LAS __attribute__((address_space(3)))
;     __device__ __forceinline__ void operator()(f32x4 (&acc)[2][2][4][2], const Unit& u, int ui, int wr, int wc, int fr_, int fq_) const {
;     ...
;             for (int m = 0; m < 4; ++m) { const float r = rtab[ui * 256 + ai * HALF + wr * 64 + m * 16 + fr];
; #pragma unroll
;                 for (int bj = 0; bj < 2; ++bj)
; #pragma unroll
;                     for (int n = 0; n < 2; ++n) acc[ai][bj][m][n] = acc[ai][bj][m][n] * r; }
;     ...
;                 for (int ai = 0; ai < 2; ++ai) { const int kb = 2 * ai + wr;
;                     f32x4 c62 = (f32x4){0.f, 0.f, 0.f, 0.f}, c63 = c62;
;                     if (kb > 0) { c62 = *(const PG8_LAS f32x4*)(exch + (((kb - 1) * 2 + 0) * 256 + bj * HALF + 32 * wc + 8 * fq + 4 * n)); c63 = *(const PG8_LAS f32x4*)(exch + (((kb - 1) * 2 + 1) * 256 + bj * HALF + 32 * wc + 8 * fq + 4 * n)); }
; #pragma unroll
;                     for (int m = 3; m >= 0; --m) { f32x4 cur = acc[ai][bj][m][n], res;
; #pragma unroll
;                         for (int j = 0; j < 4; ++j) { const float c = cur[j]; const float pv = (m > 0) ? acc[ai][bj][m > 0 ? m - 1 : 0][n][j] : (fr == 15 ? c63[j] : c62[j]); float t1, t2;
;                             asm volatile("s_nop 1\n\tv_mov_b32_dpp %0, %3 row_ror:1 row_mask:0xf bank_mask:0xf\n\tv_mov_b32_dpp %1, %3 row_ror:2 row_mask:0xf bank_mask:0xf\n\t"
;                                          "v_mov_b32_dpp %0, %2 row_shr:1 row_mask:0xf bank_mask:0xf\n\tv_mov_b32_dpp %1, %2 row_shr:2 row_mask:0xf bank_mask:0xf"
;                                          : "=&v"(t1), "=&v"(t2) : "v"(c), "v"(pv));
;                             res[j] = bb[j] + w0[j] * t2 + w1[j] * t1 + w2[j] * c; }
;                         asm volatile("" : "+v"(res[0]), "+v"(res[1]), "+v"(res[2]), "+v"(res[3]));
;                         acc[ai][bj][m][n] = res; } }
.LBB0_1196:
	v_pk_mul_f32 v[36:37], v[36:37], v[192:193] op_sel_hi:[1,0]
	v_pk_mul_f32 v[28:29], v[28:29], v[190:191] op_sel_hi:[1,0]
	v_pk_mul_f32 v[24:25], v[24:25], v[188:189] op_sel_hi:[1,0]
	v_pk_mul_f32 v[22:23], v[22:23], v[188:189]
	v_pk_mul_f32 v[26:27], v[26:27], v[190:191]
	v_pk_mul_f32 v[34:35], v[34:35], v[192:193]
	v_fma_f32 v87, v82, v74, v54
	v_fmac_f32_dpp v87, v82, v62 row_shr:2 row_mask:0xf bank_mask:0xf
	v_fmac_f32_dpp v87, v22, v62 row_shl:14 row_mask:0xf bank_mask:0xf
	v_fmac_f32_dpp v87, v82, v66 row_shr:1 row_mask:0xf bank_mask:0xf
	v_fmac_f32_dpp v87, v22, v66 row_shl:15 row_mask:0xf bank_mask:0xf
	v_fma_f32 v86, v83, v75, v55
	v_fmac_f32_dpp v86, v83, v63 row_shr:2 row_mask:0xf bank_mask:0xf
	v_fmac_f32_dpp v86, v23, v63 row_shl:14 row_mask:0xf bank_mask:0xf
	v_fmac_f32_dpp v86, v83, v67 row_shr:1 row_mask:0xf bank_mask:0xf
	v_fmac_f32_dpp v86, v23, v67 row_shl:15 row_mask:0xf bank_mask:0xf
	v_fma_f32 v82, v84, v76, v56
	v_fmac_f32_dpp v82, v84, v64 row_shr:2 row_mask:0xf bank_mask:0xf
	v_fmac_f32_dpp v82, v24, v64 row_shl:14 row_mask:0xf bank_mask:0xf
	v_fmac_f32_dpp v82, v84, v68 row_shr:1 row_mask:0xf bank_mask:0xf
	v_fmac_f32_dpp v82, v24, v68 row_shl:15 row_mask:0xf bank_mask:0xf
	v_fma_f32 v83, v85, v77, v57
	v_fmac_f32_dpp v83, v85, v65 row_shr:2 row_mask:0xf bank_mask:0xf
	v_fmac_f32_dpp v83, v25, v65 row_shl:14 row_mask:0xf bank_mask:0xf
	v_fmac_f32_dpp v83, v85, v69 row_shr:1 row_mask:0xf bank_mask:0xf
	v_fmac_f32_dpp v83, v25, v69 row_shl:15 row_mask:0xf bank_mask:0xf
	v_mov_b32_e32 v44, 0
	v_fma_f32 v89, v22, v74, v54
	v_fmac_f32_dpp v89, v22, v62 row_shr:2 row_mask:0xf bank_mask:0xf
	v_fmac_f32_dpp v89, v26, v62 row_shl:14 row_mask:0xf bank_mask:0xf
	v_fmac_f32_dpp v89, v22, v66 row_shr:1 row_mask:0xf bank_mask:0xf
	v_fmac_f32_dpp v89, v26, v66 row_shl:15 row_mask:0xf bank_mask:0xf
	v_mov_b32_e32 v45, 0
	v_fma_f32 v88, v23, v75, v55
	v_fmac_f32_dpp v88, v23, v63 row_shr:2 row_mask:0xf bank_mask:0xf
	v_fmac_f32_dpp v88, v27, v63 row_shl:14 row_mask:0xf bank_mask:0xf
	v_fmac_f32_dpp v88, v23, v67 row_shr:1 row_mask:0xf bank_mask:0xf
	v_fmac_f32_dpp v88, v27, v67 row_shl:15 row_mask:0xf bank_mask:0xf
	v_mov_b32_e32 v42, 0
	v_fma_f32 v84, v24, v76, v56
	v_fmac_f32_dpp v84, v24, v64 row_shr:2 row_mask:0xf bank_mask:0xf
	v_fmac_f32_dpp v84, v28, v64 row_shl:14 row_mask:0xf bank_mask:0xf
	v_fmac_f32_dpp v84, v24, v68 row_shr:1 row_mask:0xf bank_mask:0xf
	v_fmac_f32_dpp v84, v28, v68 row_shl:15 row_mask:0xf bank_mask:0xf
	v_fma_f32 v85, v25, v77, v57
	v_fmac_f32_dpp v85, v25, v65 row_shr:2 row_mask:0xf bank_mask:0xf
	v_fmac_f32_dpp v85, v29, v65 row_shl:14 row_mask:0xf bank_mask:0xf
	v_fmac_f32_dpp v85, v25, v69 row_shr:1 row_mask:0xf bank_mask:0xf
	v_fmac_f32_dpp v85, v29, v69 row_shl:15 row_mask:0xf bank_mask:0xf
	s_waitcnt lgkmcnt(0)
	v_cndmask_b32_e64 v25, v78, v38, s[8:9]
	v_fma_f32 v93, v26, v74, v54
	v_fmac_f32_dpp v93, v26, v62 row_shr:2 row_mask:0xf bank_mask:0xf
	v_fmac_f32_dpp v93, v34, v62 row_shl:14 row_mask:0xf bank_mask:0xf
	v_fmac_f32_dpp v93, v26, v66 row_shr:1 row_mask:0xf bank_mask:0xf
	v_fmac_f32_dpp v93, v34, v66 row_shl:15 row_mask:0xf bank_mask:0xf
	v_fma_f32 v92, v27, v75, v55
	v_fmac_f32_dpp v92, v27, v63 row_shr:2 row_mask:0xf bank_mask:0xf
	v_fmac_f32_dpp v92, v35, v63 row_shl:14 row_mask:0xf bank_mask:0xf
	v_fmac_f32_dpp v92, v27, v67 row_shr:1 row_mask:0xf bank_mask:0xf
	v_fmac_f32_dpp v92, v35, v67 row_shl:15 row_mask:0xf bank_mask:0xf
	v_fma_f32 v90, v28, v76, v56
	v_fmac_f32_dpp v90, v28, v64 row_shr:2 row_mask:0xf bank_mask:0xf
	v_fmac_f32_dpp v90, v36, v64 row_shl:14 row_mask:0xf bank_mask:0xf
	v_fmac_f32_dpp v90, v28, v68 row_shr:1 row_mask:0xf bank_mask:0xf
	v_fmac_f32_dpp v90, v36, v68 row_shl:15 row_mask:0xf bank_mask:0xf
	v_fma_f32 v91, v29, v77, v57
	v_fmac_f32_dpp v91, v29, v65 row_shr:2 row_mask:0xf bank_mask:0xf
	v_fmac_f32_dpp v91, v37, v65 row_shl:14 row_mask:0xf bank_mask:0xf
	v_fmac_f32_dpp v91, v29, v69 row_shr:1 row_mask:0xf bank_mask:0xf
	v_fmac_f32_dpp v91, v37, v69 row_shl:15 row_mask:0xf bank_mask:0xf
	v_cndmask_b32_e64 v24, v79, v39, s[8:9]
	v_fma_f32 v78, v34, v74, v54
	v_fmac_f32_dpp v78, v34, v62 row_shr:2 row_mask:0xf bank_mask:0xf
	v_fmac_f32_dpp v78, v25, v62 row_shl:14 row_mask:0xf bank_mask:0xf
	v_fmac_f32_dpp v78, v34, v66 row_shr:1 row_mask:0xf bank_mask:0xf
	v_fmac_f32_dpp v78, v25, v66 row_shl:15 row_mask:0xf bank_mask:0xf
	v_fma_f32 v229, v35, v75, v55
	v_fmac_f32_dpp v229, v35, v63 row_shr:2 row_mask:0xf bank_mask:0xf
	v_fmac_f32_dpp v229, v24, v63 row_shl:14 row_mask:0xf bank_mask:0xf
	v_fmac_f32_dpp v229, v35, v67 row_shr:1 row_mask:0xf bank_mask:0xf
	v_fmac_f32_dpp v229, v24, v67 row_shl:15 row_mask:0xf bank_mask:0xf
	v_cndmask_b32_e64 v23, v80, v40, s[8:9]
	v_cndmask_b32_e64 v22, v81, v41, s[8:9]
	v_fma_f32 v54, v36, v76, v56
	v_fmac_f32_dpp v54, v36, v64 row_shr:2 row_mask:0xf bank_mask:0xf
	v_fmac_f32_dpp v54, v23, v64 row_shl:14 row_mask:0xf bank_mask:0xf
	v_fmac_f32_dpp v54, v36, v68 row_shr:1 row_mask:0xf bank_mask:0xf
	v_fmac_f32_dpp v54, v23, v68 row_shl:15 row_mask:0xf bank_mask:0xf
	v_fma_f32 v231, v37, v77, v57
	v_fmac_f32_dpp v231, v37, v65 row_shr:2 row_mask:0xf bank_mask:0xf
	v_fmac_f32_dpp v231, v22, v65 row_shl:14 row_mask:0xf bank_mask:0xf
	v_fmac_f32_dpp v231, v37, v69 row_shr:1 row_mask:0xf bank_mask:0xf
	v_fmac_f32_dpp v231, v22, v69 row_shl:15 row_mask:0xf bank_mask:0xf
	v_mov_b32_e32 v55, v229
	v_mov_b32_e32 v57, v231
	s_waitcnt vmcnt(0)
	v_mov_b32_e32 v46, 0
	v_mov_b32_e32 v47, 0
	s_and_b64 vcc, exec, s[10:11]
	v_mov_b32_e32 v62, 0
	v_mov_b32_e32 v63, 0
	v_mov_b32_e32 v64, 0
	v_mov_b32_e32 v65, 0
	s_cbranch_vccnz .LBB0_1198
	v_add_u32_e32 v31, 0xfffffa10, v227
	v_add_u32_e32 v30, 0xfffffe10, v227
	ds_read_b128 v[44:47], v31
	ds_read_b128 v[62:65], v30
; #define PG8_LAS __attribute__((address_space(3)))
;     __device__ __forceinline__ void operator()(f32x4 (&acc)[2][2][4][2], const Unit& u, int ui, int wr, int wc, int fr_, int fq_) const {
;     ...
;             for (int m = 0; m < 4; ++m) { const float r = rtab[ui * 256 + ai * HALF + wr * 64 + m * 16 + fr];
; #pragma unroll
;                 for (int bj = 0; bj < 2; ++bj)
; #pragma unroll
;                     for (int n = 0; n < 2; ++n) acc[ai][bj][m][n] = acc[ai][bj][m][n] * r; }
;     ...
;                 for (int ai = 0; ai < 2; ++ai) { const int kb = 2 * ai + wr;
;                     f32x4 c62 = (f32x4){0.f, 0.f, 0.f, 0.f}, c63 = c62;
;                     if (kb > 0) { c62 = *(const PG8_LAS f32x4*)(exch + (((kb - 1) * 2 + 0) * 256 + bj * HALF + 32 * wc + 8 * fq + 4 * n)); c63 = *(const PG8_LAS f32x4*)(exch + (((kb - 1) * 2 + 1) * 256 + bj * HALF + 32 * wc + 8 * fq + 4 * n)); }
; #pragma unroll
;                     for (int m = 3; m >= 0; --m) { f32x4 cur = acc[ai][bj][m][n], res;
; #pragma unroll
;                         for (int j = 0; j < 4; ++j) { const float c = cur[j]; const float pv = (m > 0) ? acc[ai][bj][m > 0 ? m - 1 : 0][n][j] : (fr == 15 ? c63[j] : c62[j]); float t1, t2;
;                             asm volatile("s_nop 1\n\tv_mov_b32_dpp %0, %3 row_ror:1 row_mask:0xf bank_mask:0xf\n\tv_mov_b32_dpp %1, %3 row_ror:2 row_mask:0xf bank_mask:0xf\n\t"
;                                          "v_mov_b32_dpp %0, %2 row_shr:1 row_mask:0xf bank_mask:0xf\n\tv_mov_b32_dpp %1, %2 row_shr:2 row_mask:0xf bank_mask:0xf"
;                                          : "=&v"(t1), "=&v"(t2) : "v"(c), "v"(pv));
;                             res[j] = bb[j] + w0[j] * t2 + w1[j] * t1 + w2[j] * c; }
;                         asm volatile("" : "+v"(res[0]), "+v"(res[1]), "+v"(res[2]), "+v"(res[3]));
;                         acc[ai][bj][m][n] = res; } }
.LBB0_1198:
	v_pk_mul_f32 v[76:77], v[18:19], v[194:195]
	v_pk_mul_f32 v[74:75], v[20:21], v[194:195] op_sel_hi:[1,0]
	v_pk_mul_f32 v[16:17], v[16:17], v[196:197] op_sel_hi:[1,0]
	v_pk_mul_f32 v[14:15], v[14:15], v[196:197]
	s_and_b64 vcc, exec, s[12:13]
	s_waitcnt vmcnt(0)
	v_fma_f32 v20, v70, v244, v248
	v_fmac_f32_dpp v20, v70, v234 row_shr:2 row_mask:0xf bank_mask:0xf
	v_fmac_f32_dpp v20, v14, v234 row_shl:14 row_mask:0xf bank_mask:0xf
	v_fmac_f32_dpp v20, v70, v240 row_shr:1 row_mask:0xf bank_mask:0xf
	v_fmac_f32_dpp v20, v14, v240 row_shl:15 row_mask:0xf bank_mask:0xf
	v_fma_f32 v18, v71, v245, v249
	v_fmac_f32_dpp v18, v71, v235 row_shr:2 row_mask:0xf bank_mask:0xf
	v_fmac_f32_dpp v18, v15, v235 row_shl:14 row_mask:0xf bank_mask:0xf
	v_fmac_f32_dpp v18, v71, v241 row_shr:1 row_mask:0xf bank_mask:0xf
	v_fmac_f32_dpp v18, v15, v241 row_shl:15 row_mask:0xf bank_mask:0xf
	v_fma_f32 v19, v72, v246, v250
	v_fmac_f32_dpp v19, v72, v236 row_shr:2 row_mask:0xf bank_mask:0xf
	v_fmac_f32_dpp v19, v16, v236 row_shl:14 row_mask:0xf bank_mask:0xf
	v_fmac_f32_dpp v19, v72, v242 row_shr:1 row_mask:0xf bank_mask:0xf
	v_fmac_f32_dpp v19, v16, v242 row_shl:15 row_mask:0xf bank_mask:0xf
	v_fma_f32 v21, v73, v247, v251
	v_fmac_f32_dpp v21, v73, v237 row_shr:2 row_mask:0xf bank_mask:0xf
	v_fmac_f32_dpp v21, v17, v237 row_shl:14 row_mask:0xf bank_mask:0xf
	v_fmac_f32_dpp v21, v73, v243 row_shr:1 row_mask:0xf bank_mask:0xf
	v_fmac_f32_dpp v21, v17, v243 row_shl:15 row_mask:0xf bank_mask:0xf
	s_nop 0
	v_fma_f32 v56, v14, v244, v248
	v_fmac_f32_dpp v56, v14, v234 row_shr:2 row_mask:0xf bank_mask:0xf
	v_fmac_f32_dpp v56, v76, v234 row_shl:14 row_mask:0xf bank_mask:0xf
	v_fmac_f32_dpp v56, v14, v240 row_shr:1 row_mask:0xf bank_mask:0xf
	v_fmac_f32_dpp v56, v76, v240 row_shl:15 row_mask:0xf bank_mask:0xf
	s_nop 0
	v_fma_f32 v30, v15, v245, v249
	v_fmac_f32_dpp v30, v15, v235 row_shr:2 row_mask:0xf bank_mask:0xf
	v_fmac_f32_dpp v30, v77, v235 row_shl:14 row_mask:0xf bank_mask:0xf
	v_fmac_f32_dpp v30, v15, v241 row_shr:1 row_mask:0xf bank_mask:0xf
	v_fmac_f32_dpp v30, v77, v241 row_shl:15 row_mask:0xf bank_mask:0xf
	s_nop 0
	v_fma_f32 v31, v16, v246, v250
	v_fmac_f32_dpp v31, v16, v236 row_shr:2 row_mask:0xf bank_mask:0xf
	v_fmac_f32_dpp v31, v74, v236 row_shl:14 row_mask:0xf bank_mask:0xf
	v_fmac_f32_dpp v31, v16, v242 row_shr:1 row_mask:0xf bank_mask:0xf
	v_fmac_f32_dpp v31, v74, v242 row_shl:15 row_mask:0xf bank_mask:0xf
	v_fma_f32 v66, v17, v247, v251
	v_fmac_f32_dpp v66, v17, v237 row_shr:2 row_mask:0xf bank_mask:0xf
	v_fmac_f32_dpp v66, v75, v237 row_shl:14 row_mask:0xf bank_mask:0xf
	v_fmac_f32_dpp v66, v17, v243 row_shr:1 row_mask:0xf bank_mask:0xf
	v_fmac_f32_dpp v66, v75, v243 row_shl:15 row_mask:0xf bank_mask:0xf
	s_waitcnt lgkmcnt(0)
	v_cndmask_b32_e64 v17, v44, v62, s[8:9]
	v_fma_f32 v69, v76, v244, v248
	v_fmac_f32_dpp v69, v76, v234 row_shr:2 row_mask:0xf bank_mask:0xf
	v_fmac_f32_dpp v69, v58, v234 row_shl:14 row_mask:0xf bank_mask:0xf
	v_fmac_f32_dpp v69, v76, v240 row_shr:1 row_mask:0xf bank_mask:0xf
	v_fmac_f32_dpp v69, v58, v240 row_shl:15 row_mask:0xf bank_mask:0xf
	v_fma_f32 v67, v77, v245, v249
	v_fmac_f32_dpp v67, v77, v235 row_shr:2 row_mask:0xf bank_mask:0xf
	v_fmac_f32_dpp v67, v59, v235 row_shl:14 row_mask:0xf bank_mask:0xf
	v_fmac_f32_dpp v67, v77, v241 row_shr:1 row_mask:0xf bank_mask:0xf
	v_fmac_f32_dpp v67, v59, v241 row_shl:15 row_mask:0xf bank_mask:0xf
	v_fma_f32 v68, v74, v246, v250
	v_fmac_f32_dpp v68, v74, v236 row_shr:2 row_mask:0xf bank_mask:0xf
	v_fmac_f32_dpp v68, v60, v236 row_shl:14 row_mask:0xf bank_mask:0xf
	v_fmac_f32_dpp v68, v74, v242 row_shr:1 row_mask:0xf bank_mask:0xf
	v_fmac_f32_dpp v68, v60, v242 row_shl:15 row_mask:0xf bank_mask:0xf
	v_fma_f32 v70, v75, v247, v251
	v_fmac_f32_dpp v70, v75, v237 row_shr:2 row_mask:0xf bank_mask:0xf
	v_fmac_f32_dpp v70, v61, v237 row_shl:14 row_mask:0xf bank_mask:0xf
	v_fmac_f32_dpp v70, v75, v243 row_shr:1 row_mask:0xf bank_mask:0xf
	v_fmac_f32_dpp v70, v61, v243 row_shl:15 row_mask:0xf bank_mask:0xf
	v_cndmask_b32_e64 v16, v45, v63, s[8:9]
	v_fma_f32 v62, v58, v244, v248
	v_fmac_f32_dpp v62, v58, v234 row_shr:2 row_mask:0xf bank_mask:0xf
	v_fmac_f32_dpp v62, v17, v234 row_shl:14 row_mask:0xf bank_mask:0xf
	v_fmac_f32_dpp v62, v58, v240 row_shr:1 row_mask:0xf bank_mask:0xf
	v_fmac_f32_dpp v62, v17, v240 row_shl:15 row_mask:0xf bank_mask:0xf
	v_cndmask_b32_e64 v15, v46, v64, s[8:9]
	v_fma_f32 v58, v59, v245, v249
	v_fmac_f32_dpp v58, v59, v235 row_shr:2 row_mask:0xf bank_mask:0xf
	v_fmac_f32_dpp v58, v16, v235 row_shl:14 row_mask:0xf bank_mask:0xf
	v_fmac_f32_dpp v58, v59, v241 row_shr:1 row_mask:0xf bank_mask:0xf
	v_fmac_f32_dpp v58, v16, v241 row_shl:15 row_mask:0xf bank_mask:0xf
	v_cndmask_b32_e64 v14, v47, v65, s[8:9]
	v_fma_f32 v59, v60, v246, v250
	v_fmac_f32_dpp v59, v60, v236 row_shr:2 row_mask:0xf bank_mask:0xf
	v_fmac_f32_dpp v59, v15, v236 row_shl:14 row_mask:0xf bank_mask:0xf
	v_fmac_f32_dpp v59, v60, v242 row_shr:1 row_mask:0xf bank_mask:0xf
	v_fmac_f32_dpp v59, v15, v242 row_shl:15 row_mask:0xf bank_mask:0xf
	v_mov_b32_e32 v43, 0
	v_fma_f32 v60, v61, v247, v251
	v_fmac_f32_dpp v60, v61, v237 row_shr:2 row_mask:0xf bank_mask:0xf
	v_fmac_f32_dpp v60, v14, v237 row_shl:14 row_mask:0xf bank_mask:0xf
	v_fmac_f32_dpp v60, v61, v243 row_shr:1 row_mask:0xf bank_mask:0xf
	v_fmac_f32_dpp v60, v14, v243 row_shl:15 row_mask:0xf bank_mask:0xf
	v_mov_b32_e32 v44, 0
	v_mov_b32_e32 v45, 0
	v_mov_b32_e32 v14, 0
	v_mov_b32_e32 v15, 0
	v_mov_b32_e32 v16, 0
	v_mov_b32_e32 v17, 0
	s_cbranch_vccnz .LBB0_1200
	ds_read_b128 v[42:45], v227 offset:2576
	ds_read_b128 v[14:17], v227 offset:3600
; #define PG8_LAS __attribute__((address_space(3)))
;     __device__ __forceinline__ void operator()(f32x4 (&acc)[2][2][4][2], const Unit& u, int ui, int wr, int wc, int fr_, int fq_) const {
;     ...
;             for (int m = 0; m < 4; ++m) { const float r = rtab[ui * 256 + ai * HALF + wr * 64 + m * 16 + fr];
; #pragma unroll
;                 for (int bj = 0; bj < 2; ++bj)
; #pragma unroll
;                     for (int n = 0; n < 2; ++n) acc[ai][bj][m][n] = acc[ai][bj][m][n] * r; }
;     ...
;                 for (int ai = 0; ai < 2; ++ai) { const int kb = 2 * ai + wr;
;                     f32x4 c62 = (f32x4){0.f, 0.f, 0.f, 0.f}, c63 = c62;
;                     if (kb > 0) { c62 = *(const PG8_LAS f32x4*)(exch + (((kb - 1) * 2 + 0) * 256 + bj * HALF + 32 * wc + 8 * fq + 4 * n)); c63 = *(const PG8_LAS f32x4*)(exch + (((kb - 1) * 2 + 1) * 256 + bj * HALF + 32 * wc + 8 * fq + 4 * n)); }
; #pragma unroll
;                     for (int m = 3; m >= 0; --m) { f32x4 cur = acc[ai][bj][m][n], res;
; #pragma unroll
;                         for (int j = 0; j < 4; ++j) { const float c = cur[j]; const float pv = (m > 0) ? acc[ai][bj][m > 0 ? m - 1 : 0][n][j] : (fr == 15 ? c63[j] : c62[j]); float t1, t2;
;                             asm volatile("s_nop 1\n\tv_mov_b32_dpp %0, %3 row_ror:1 row_mask:0xf bank_mask:0xf\n\tv_mov_b32_dpp %1, %3 row_ror:2 row_mask:0xf bank_mask:0xf\n\t"
;                                          "v_mov_b32_dpp %0, %2 row_shr:1 row_mask:0xf bank_mask:0xf\n\tv_mov_b32_dpp %1, %2 row_shr:2 row_mask:0xf bank_mask:0xf"
;                                          : "=&v"(t1), "=&v"(t2) : "v"(c), "v"(pv));
;                             res[j] = bb[j] + w0[j] * t2 + w1[j] * t1 + w2[j] * c; }
;                         asm volatile("" : "+v"(res[0]), "+v"(res[1]), "+v"(res[2]), "+v"(res[3]));
;                         acc[ai][bj][m][n] = res; } }
;     ...
;                     for (int j = 0; j < 4; ++j) { const float g = acc[ai][0][m][n][j], up = acc[ai][1][m][n][j]; gv[n * 4 + j] = g * __builtin_amdgcn_rcpf(1.0f + __builtin_amdgcn_exp2f(g * -1.4426950408889634f)) * up; }
.LBB0_1200:
	v_pk_mul_f32 v[76:77], v[6:7], v[190:191]
	v_pk_mul_f32 v[72:73], v[10:11], v[192:193]
	v_pk_mul_f32 v[4:5], v[4:5], v[188:189] op_sel_hi:[1,0]
	v_pk_mul_f32 v[2:3], v[2:3], v[188:189]
	v_pk_mul_f32 v[74:75], v[8:9], v[190:191] op_sel_hi:[1,0]
	v_fma_f32 v7, v50, v244, v248
	v_fmac_f32_dpp v7, v50, v234 row_shr:2 row_mask:0xf bank_mask:0xf
	v_fmac_f32_dpp v7, v2, v234 row_shl:14 row_mask:0xf bank_mask:0xf
	v_fmac_f32_dpp v7, v50, v240 row_shr:1 row_mask:0xf bank_mask:0xf
	v_fmac_f32_dpp v7, v2, v240 row_shl:15 row_mask:0xf bank_mask:0xf
	v_fma_f32 v6, v51, v245, v249
	v_fmac_f32_dpp v6, v51, v235 row_shr:2 row_mask:0xf bank_mask:0xf
	v_fmac_f32_dpp v6, v3, v235 row_shl:14 row_mask:0xf bank_mask:0xf
	v_fmac_f32_dpp v6, v51, v241 row_shr:1 row_mask:0xf bank_mask:0xf
	v_fmac_f32_dpp v6, v3, v241 row_shl:15 row_mask:0xf bank_mask:0xf
	v_mov_b32_e32 v46, v192
	v_mov_b32_e32 v47, v192
	v_pk_mul_f32 v[64:65], v[12:13], v[46:47]
	v_fma_f32 v8, v52, v246, v250
	v_fmac_f32_dpp v8, v52, v236 row_shr:2 row_mask:0xf bank_mask:0xf
	v_fmac_f32_dpp v8, v4, v236 row_shl:14 row_mask:0xf bank_mask:0xf
	v_fmac_f32_dpp v8, v52, v242 row_shr:1 row_mask:0xf bank_mask:0xf
	v_fmac_f32_dpp v8, v4, v242 row_shl:15 row_mask:0xf bank_mask:0xf
	v_fma_f32 v9, v53, v247, v251
	v_fmac_f32_dpp v9, v53, v237 row_shr:2 row_mask:0xf bank_mask:0xf
	v_fmac_f32_dpp v9, v5, v237 row_shl:14 row_mask:0xf bank_mask:0xf
	v_fmac_f32_dpp v9, v53, v243 row_shr:1 row_mask:0xf bank_mask:0xf
	v_fmac_f32_dpp v9, v5, v243 row_shl:15 row_mask:0xf bank_mask:0xf
	v_fma_f32 v11, v2, v244, v248
	v_fmac_f32_dpp v11, v2, v234 row_shr:2 row_mask:0xf bank_mask:0xf
	v_fmac_f32_dpp v11, v76, v234 row_shl:14 row_mask:0xf bank_mask:0xf
	v_fmac_f32_dpp v11, v2, v240 row_shr:1 row_mask:0xf bank_mask:0xf
	v_fmac_f32_dpp v11, v76, v240 row_shl:15 row_mask:0xf bank_mask:0xf
	s_waitcnt lgkmcnt(0)
	v_cndmask_b32_e64 v17, v45, v17, s[8:9]
	v_mov_b32_e32 v2, v3
	v_fma_f32 v10, v2, v245, v249
	s_nop 0
	v_fmac_f32_dpp v10, v2, v235 row_shr:2 row_mask:0xf bank_mask:0xf
	v_fmac_f32_dpp v10, v77, v235 row_shl:14 row_mask:0xf bank_mask:0xf
	v_fmac_f32_dpp v10, v2, v241 row_shr:1 row_mask:0xf bank_mask:0xf
	v_fmac_f32_dpp v10, v77, v241 row_shl:15 row_mask:0xf bank_mask:0xf
	v_fma_f32 v12, v4, v246, v250
	v_fmac_f32_dpp v12, v4, v236 row_shr:2 row_mask:0xf bank_mask:0xf
	v_fmac_f32_dpp v12, v74, v236 row_shl:14 row_mask:0xf bank_mask:0xf
	v_fmac_f32_dpp v12, v4, v242 row_shr:1 row_mask:0xf bank_mask:0xf
	v_fmac_f32_dpp v12, v74, v242 row_shl:15 row_mask:0xf bank_mask:0xf
	v_mov_b32_e32 v4, v5
	v_fma_f32 v13, v4, v247, v251
	s_nop 0
	v_fmac_f32_dpp v13, v4, v237 row_shr:2 row_mask:0xf bank_mask:0xf
	v_fmac_f32_dpp v13, v75, v237 row_shl:14 row_mask:0xf bank_mask:0xf
	v_fmac_f32_dpp v13, v4, v243 row_shr:1 row_mask:0xf bank_mask:0xf
	v_fmac_f32_dpp v13, v75, v243 row_shl:15 row_mask:0xf bank_mask:0xf
	v_fma_f32 v47, v76, v244, v248
	v_fmac_f32_dpp v47, v76, v234 row_shr:2 row_mask:0xf bank_mask:0xf
	v_fmac_f32_dpp v47, v72, v234 row_shl:14 row_mask:0xf bank_mask:0xf
	v_fmac_f32_dpp v47, v76, v240 row_shr:1 row_mask:0xf bank_mask:0xf
	v_fmac_f32_dpp v47, v72, v240 row_shl:15 row_mask:0xf bank_mask:0xf
	v_fma_f32 v46, v77, v245, v249
	v_fmac_f32_dpp v46, v77, v235 row_shr:2 row_mask:0xf bank_mask:0xf
	v_fmac_f32_dpp v46, v73, v235 row_shl:14 row_mask:0xf bank_mask:0xf
	v_fmac_f32_dpp v46, v77, v241 row_shr:1 row_mask:0xf bank_mask:0xf
	v_fmac_f32_dpp v46, v73, v241 row_shl:15 row_mask:0xf bank_mask:0xf
	v_fma_f32 v50, v74, v246, v250
	v_fmac_f32_dpp v50, v74, v236 row_shr:2 row_mask:0xf bank_mask:0xf
	v_fmac_f32_dpp v50, v64, v236 row_shl:14 row_mask:0xf bank_mask:0xf
	v_fmac_f32_dpp v50, v74, v242 row_shr:1 row_mask:0xf bank_mask:0xf
	v_fmac_f32_dpp v50, v64, v242 row_shl:15 row_mask:0xf bank_mask:0xf
	v_fma_f32 v51, v75, v247, v251
	v_fmac_f32_dpp v51, v75, v237 row_shr:2 row_mask:0xf bank_mask:0xf
	v_fmac_f32_dpp v51, v65, v237 row_shl:14 row_mask:0xf bank_mask:0xf
	v_fmac_f32_dpp v51, v75, v243 row_shr:1 row_mask:0xf bank_mask:0xf
	v_fmac_f32_dpp v51, v65, v243 row_shl:15 row_mask:0xf bank_mask:0xf
	v_cndmask_b32_e64 v4, v43, v15, s[8:9]
	v_cndmask_b32_e64 v3, v42, v14, s[8:9]
	v_cndmask_b32_e64 v2, v44, v16, s[8:9]
	v_fma_f32 v252, v72, v244, v248
	v_fmac_f32_dpp v252, v72, v234 row_shr:2 row_mask:0xf bank_mask:0xf
	v_fmac_f32_dpp v252, v3, v234 row_shl:14 row_mask:0xf bank_mask:0xf
	v_fmac_f32_dpp v252, v72, v240 row_shr:1 row_mask:0xf bank_mask:0xf
	v_fmac_f32_dpp v252, v3, v240 row_shl:15 row_mask:0xf bank_mask:0xf
	v_fma_f32 v231, v73, v245, v249
	v_fmac_f32_dpp v231, v73, v235 row_shr:2 row_mask:0xf bank_mask:0xf
	v_fmac_f32_dpp v231, v4, v235 row_shl:14 row_mask:0xf bank_mask:0xf
	v_fmac_f32_dpp v231, v73, v241 row_shr:1 row_mask:0xf bank_mask:0xf
	v_fmac_f32_dpp v231, v4, v241 row_shl:15 row_mask:0xf bank_mask:0xf
	v_fma_f32 v15, v64, v246, v250
	v_fmac_f32_dpp v15, v64, v236 row_shr:2 row_mask:0xf bank_mask:0xf
	v_fmac_f32_dpp v15, v2, v236 row_shl:14 row_mask:0xf bank_mask:0xf
	v_fmac_f32_dpp v15, v64, v242 row_shr:1 row_mask:0xf bank_mask:0xf
	v_fmac_f32_dpp v15, v2, v242 row_shl:15 row_mask:0xf bank_mask:0xf
	v_mov_b32_e32 v27, v231
	v_mov_b32_e32 v26, v252
	v_fma_f32 v28, v65, v247, v251
	v_fmac_f32_dpp v28, v65, v237 row_shr:2 row_mask:0xf bank_mask:0xf
	v_fmac_f32_dpp v28, v17, v237 row_shl:14 row_mask:0xf bank_mask:0xf
	v_fmac_f32_dpp v28, v65, v243 row_shr:1 row_mask:0xf bank_mask:0xf
	v_fmac_f32_dpp v28, v17, v243 row_shl:15 row_mask:0xf bank_mask:0xf
	v_mul_f32_e32 v22, s98, v123
	v_mul_f32_e32 v2, s98, v223
	v_mul_f32_e32 v3, s98, v224
	v_exp_f32_e32 v2, v2
	v_exp_f32_e32 v3, v3
; __device__ __forceinline__ unsigned cvt_pk_bf16(float lo, float hi) { unsigned r; asm volatile("v_cvt_pk_bf16_f32 %0, %1, %2" : "=v"(r) : "v"(lo), "v"(hi)); return r; }
;     __device__ __forceinline__ void operator()(f32x4 (&acc)[2][2][4][2], const Unit& u, int ui, int wr, int wc, int fr_, int fq_) const {
;     ...
;         const int row0 = u.pm * BM + wr * 64 + fr;
; #pragma unroll
;         for (int ai = 0; ai < 2; ++ai)
; #pragma unroll
;             for (int m = 0; m < 4; ++m) { float gv[8];
; #pragma unroll
;                 for (int n = 0; n < 2; ++n)
; #pragma unroll
;                     for (int j = 0; j < 4; ++j) { const float g = acc[ai][0][m][n][j], up = acc[ai][1][m][n][j]; gv[n * 4 + j] = g * __builtin_amdgcn_rcpf(1.0f + __builtin_amdgcn_exp2f(g * -1.4426950408889634f)) * up; }
;                 u32x4 w; w.x = cvt_pk_bf16(gv[0], gv[1]); w.y = cvt_pk_bf16(gv[2], gv[3]); w.z = cvt_pk_bf16(gv[4], gv[5]); w.w = cvt_pk_bf16(gv[6], gv[7]);
;                 *(u32x4*)(G + (size_t)(row0 + ai * HALF + m * 16) * 2816 + fbase) = w; asm volatile("" ::: "memory"); }
	v_mul_f32_e32 v4, s98, v221
	v_mul_f32_e32 v5, s98, v222
	v_mul_f32_e32 v16, s98, v126
	v_mul_f32_e32 v17, s98, v122
	v_exp_f32_e32 v22, v22
	v_mul_f32_e32 v23, s98, v124
	v_exp_f32_e32 v4, v4
	v_exp_f32_e32 v5, v5
	v_exp_f32_e32 v16, v16
	v_exp_f32_e32 v17, v17
	v_exp_f32_e32 v23, v23
	v_add_f32_e32 v2, 1.0, v2
	v_add_f32_e32 v3, 1.0, v3
	v_add_f32_e32 v22, 1.0, v22
	v_rcp_f32_e32 v2, v2
	v_rcp_f32_e32 v3, v3
	v_add_f32_e32 v4, 1.0, v4
	v_add_f32_e32 v5, 1.0, v5
	v_add_f32_e32 v16, 1.0, v16
	v_add_f32_e32 v17, 1.0, v17
	v_rcp_f32_e32 v22, v22
	v_add_f32_e32 v23, 1.0, v23
	v_rcp_f32_e32 v4, v4
	v_rcp_f32_e32 v5, v5
	v_rcp_f32_e32 v16, v16
	v_rcp_f32_e32 v17, v17
	v_rcp_f32_e32 v23, v23
	s_lshl_b32 s0, s76, 8
	v_mul_f32_e32 v2, v223, v2
	v_mul_f32_e32 v3, v224, v3
	v_mul_f32_e32 v22, v123, v22
	s_add_i32 s0, s0, s68
	v_mul_f32_e32 v2, v2, v97
	v_mul_f32_e32 v3, v3, v96
	v_mul_f32_e32 v4, v221, v4
	v_mul_f32_e32 v5, v222, v5
	v_mul_f32_e32 v16, v126, v16
	v_mul_f32_e32 v17, v122, v17
	v_mul_f32_e32 v25, v22, v59
	v_mul_f32_e32 v22, v124, v23
	v_add_u32_e32 v14, s0, v210
	v_mul_f32_e32 v4, v4, v95
	v_mul_f32_e32 v5, v5, v94
	v_mul_f32_e32 v16, v16, v62
	v_mul_f32_e32 v17, v17, v58
	v_mul_f32_e32 v29, v22, v60
	v_cvt_pk_bf16_f32 v22, v2, v3
	v_mov_b64_e32 v[2:3], s[38:39]
	v_cvt_pk_bf16_f32 v23, v4, v5
	v_cvt_pk_bf16_f32 v24, v16, v17
	v_mad_i64_i32 v[16:17], s[0:1], v14, s83, v[2:3]
	v_lshlrev_b64 v[4:5], 1, v[186:187]
	v_lshl_add_u64 v[16:17], v[16:17], 0, v[4:5]
	v_cvt_pk_bf16_f32 v25, v25, v29
	global_store_dwordx4 v[16:17], v[22:25], off
	v_mul_f32_e32 v29, s98, v218
	v_exp_f32_e32 v29, v29
	v_mul_f32_e32 v22, s98, v217
	v_exp_f32_e32 v22, v22
	v_mul_f32_e32 v23, s98, v219
	v_exp_f32_e32 v23, v23
	v_mul_f32_e32 v24, s98, v225
	v_add_f32_e32 v22, 1.0, v22
	v_rcp_f32_e32 v22, v22
	v_add_f32_e32 v23, 1.0, v23
	v_rcp_f32_e32 v23, v23
	v_exp_f32_e32 v24, v24
	v_mul_f32_e32 v22, v217, v22
	v_mul_f32_e32 v25, v22, v108
	v_mul_f32_e32 v22, v219, v23
	v_add_f32_e32 v23, 1.0, v24
	v_mul_f32_e32 v34, s98, v220
	v_rcp_f32_e32 v23, v23
	v_mul_f32_e32 v24, s98, v144
	v_exp_f32_e32 v34, v34
	v_exp_f32_e32 v24, v24
	v_add_f32_e32 v16, 1.0, v29
	v_mul_f32_e32 v29, v22, v109
	v_mul_f32_e32 v22, v225, v23
	v_mul_f32_e32 v23, s98, v145
	v_add_f32_e32 v17, 1.0, v34
	v_mul_f32_e32 v34, v22, v69
	v_add_f32_e32 v22, 1.0, v24
	v_exp_f32_e32 v23, v23
	v_mul_f32_e32 v24, s98, v226
	v_exp_f32_e32 v24, v24
	v_rcp_f32_e32 v22, v22
	v_add_f32_e32 v23, 1.0, v23
	v_rcp_f32_e32 v16, v16
	v_rcp_f32_e32 v23, v23
	v_add_f32_e32 v24, 1.0, v24
	v_rcp_f32_e32 v17, v17
	v_rcp_f32_e32 v24, v24
	v_mul_f32_e32 v22, v144, v22
	v_mul_f32_e32 v16, v218, v16
	v_mul_f32_e32 v35, v22, v67
	v_mul_f32_e32 v22, v145, v23
	v_mul_f32_e32 v16, v16, v127
	v_mul_f32_e32 v17, v220, v17
	v_mul_f32_e32 v36, v22, v68
	v_mul_f32_e32 v22, v226, v24
	v_mul_f32_e32 v17, v17, v125
	v_mul_f32_e32 v37, v22, v70
	v_cvt_pk_bf16_f32 v22, v16, v17
	v_add_u32_e32 v16, 16, v14
	v_mad_i64_i32 v[16:17], s[0:1], v16, s83, v[2:3]
	v_lshl_add_u64 v[16:17], v[16:17], 0, v[4:5]
	v_cvt_pk_bf16_f32 v23, v25, v29
	v_cvt_pk_bf16_f32 v24, v34, v35
	v_cvt_pk_bf16_f32 v25, v36, v37
	global_store_dwordx4 v[16:17], v[22:25], off
	v_mul_f32_e32 v29, s98, v213
	v_exp_f32_e32 v29, v29
	v_mul_f32_e32 v22, s98, v154
	v_exp_f32_e32 v22, v22
	v_mul_f32_e32 v23, s98, v214
	v_exp_f32_e32 v23, v23
	v_mul_f32_e32 v24, s98, v142
	v_add_f32_e32 v22, 1.0, v22
	v_rcp_f32_e32 v22, v22
	v_add_f32_e32 v23, 1.0, v23
	v_rcp_f32_e32 v23, v23
	v_exp_f32_e32 v24, v24
	v_mul_f32_e32 v22, v154, v22
	v_mul_f32_e32 v25, v22, v100
	v_mul_f32_e32 v22, v214, v23
	v_add_f32_e32 v23, 1.0, v24
	v_mul_f32_e32 v34, s98, v216
	v_rcp_f32_e32 v23, v23
	v_mul_f32_e32 v24, s98, v136
	v_exp_f32_e32 v34, v34
	v_exp_f32_e32 v24, v24
	v_add_f32_e32 v16, 1.0, v29
	v_mul_f32_e32 v29, v22, v101
	v_mul_f32_e32 v22, v142, v23
	v_mul_f32_e32 v23, s98, v137
	v_add_f32_e32 v17, 1.0, v34
	v_mul_f32_e32 v34, v22, v56
	v_add_f32_e32 v22, 1.0, v24
	v_exp_f32_e32 v23, v23
	v_mul_f32_e32 v24, s98, v143
	v_exp_f32_e32 v24, v24
	v_rcp_f32_e32 v22, v22
	v_add_f32_e32 v23, 1.0, v23
	v_rcp_f32_e32 v16, v16
	v_rcp_f32_e32 v23, v23
	v_add_f32_e32 v24, 1.0, v24
	v_rcp_f32_e32 v17, v17
	v_rcp_f32_e32 v24, v24
	v_mul_f32_e32 v22, v136, v22
	v_mul_f32_e32 v16, v213, v16
	v_mul_f32_e32 v30, v22, v30
	v_mul_f32_e32 v22, v137, v23
	v_mul_f32_e32 v16, v16, v107
	v_mul_f32_e32 v17, v216, v17
	v_mul_f32_e32 v31, v22, v31
	v_mul_f32_e32 v22, v143, v24
	v_mul_f32_e32 v17, v17, v105
	v_mul_f32_e32 v35, v22, v66
	v_cvt_pk_bf16_f32 v22, v16, v17
	v_add_u32_e32 v16, 32, v14
	v_mad_i64_i32 v[16:17], s[0:1], v16, s83, v[2:3]
	v_cvt_pk_bf16_f32 v23, v25, v29
	v_cvt_pk_bf16_f32 v24, v34, v30
	v_lshl_add_u64 v[16:17], v[16:17], 0, v[4:5]
	v_cvt_pk_bf16_f32 v25, v31, v35
	global_store_dwordx4 v[16:17], v[22:25], off
	v_mul_f32_e32 v29, s98, v211
	v_exp_f32_e32 v29, v29
	v_mul_f32_e32 v24, s98, v133
	v_exp_f32_e32 v24, v24
	v_mul_f32_e32 v25, s98, v131
	v_exp_f32_e32 v25, v25
	v_mul_f32_e32 v30, s98, v212
	v_add_f32_e32 v24, 1.0, v24
	v_rcp_f32_e32 v24, v24
	v_exp_f32_e32 v30, v30
	v_add_f32_e32 v16, 1.0, v29
	v_mul_f32_e32 v22, s98, v152
	v_mul_f32_e32 v24, v133, v24
	v_mul_f32_e32 v20, v24, v20
	v_add_f32_e32 v24, 1.0, v25
	v_mul_f32_e32 v25, s98, v132
	v_mul_f32_e32 v23, s98, v153
	v_exp_f32_e32 v25, v25
	v_mul_f32_e32 v29, s98, v135
	v_exp_f32_e32 v22, v22
	v_exp_f32_e32 v23, v23
	v_exp_f32_e32 v29, v29
	v_add_f32_e32 v17, 1.0, v30
	v_rcp_f32_e32 v24, v24
	v_add_f32_e32 v25, 1.0, v25
	v_rcp_f32_e32 v16, v16
	v_rcp_f32_e32 v17, v17
	v_add_f32_e32 v22, 1.0, v22
	v_add_f32_e32 v23, 1.0, v23
	v_rcp_f32_e32 v25, v25
; __device__ __forceinline__ unsigned cvt_pk_bf16(float lo, float hi) { unsigned r; asm volatile("v_cvt_pk_bf16_f32 %0, %1, %2" : "=v"(r) : "v"(lo), "v"(hi)); return r; }
;     __device__ __forceinline__ void operator()(f32x4 (&acc)[2][2][4][2], const Unit& u, int ui, int wr, int wc, int fr_, int fq_) const {
;     ...
;         const int row0 = u.pm * BM + wr * 64 + fr;
; #pragma unroll
;         for (int ai = 0; ai < 2; ++ai)
; #pragma unroll
;             for (int m = 0; m < 4; ++m) { float gv[8];
; #pragma unroll
;                 for (int n = 0; n < 2; ++n)
; #pragma unroll
;                     for (int j = 0; j < 4; ++j) { const float g = acc[ai][0][m][n][j], up = acc[ai][1][m][n][j]; gv[n * 4 + j] = g * __builtin_amdgcn_rcpf(1.0f + __builtin_amdgcn_exp2f(g * -1.4426950408889634f)) * up; }
;                 u32x4 w; w.x = cvt_pk_bf16(gv[0], gv[1]); w.y = cvt_pk_bf16(gv[2], gv[3]); w.z = cvt_pk_bf16(gv[4], gv[5]); w.w = cvt_pk_bf16(gv[6], gv[7]);
;                 *(u32x4*)(G + (size_t)(row0 + ai * HALF + m * 16) * 2816 + fbase) = w; asm volatile("" ::: "memory"); }
	v_add_f32_e32 v29, 1.0, v29
	v_rcp_f32_e32 v22, v22
	v_rcp_f32_e32 v23, v23
	v_rcp_f32_e32 v29, v29
	v_mul_f32_e32 v24, v131, v24
	v_mul_f32_e32 v16, v211, v16
	v_mul_f32_e32 v17, v212, v17
	v_mul_f32_e32 v18, v24, v18
	v_mul_f32_e32 v24, v132, v25
	v_mul_f32_e32 v16, v16, v104
	v_mul_f32_e32 v17, v17, v103
	v_mul_f32_e32 v22, v152, v22
	v_mul_f32_e32 v23, v153, v23
	v_mul_f32_e32 v19, v24, v19
	v_mul_f32_e32 v24, v135, v29
	v_mul_f32_e32 v22, v22, v98
	v_mul_f32_e32 v23, v23, v99
	v_mul_f32_e32 v21, v24, v21
	v_cvt_pk_bf16_f32 v16, v16, v17
	v_cvt_pk_bf16_f32 v17, v22, v23
	v_cvt_pk_bf16_f32 v18, v20, v18
	v_add_u32_e32 v20, 48, v14
	v_cvt_pk_bf16_f32 v19, v19, v21
	v_mad_i64_i32 v[20:21], s[0:1], v20, s83, v[2:3]
	v_lshl_add_u64 v[20:21], v[20:21], 0, v[4:5]
	global_store_dwordx4 v[20:21], v[16:19], off
	v_mul_f32_e32 v22, s98, v102
	v_mul_f32_e32 v21, s98, v106
	v_mul_f32_e32 v16, s98, v134
	v_mul_f32_e32 v17, s98, v130
	v_mul_f32_e32 v18, s98, v32
	v_exp_f32_e32 v16, v16
	v_exp_f32_e32 v17, v17
	v_exp_f32_e32 v18, v18
	v_mul_f32_e32 v19, s98, v33
	v_exp_f32_e32 v22, v22
	v_exp_f32_e32 v19, v19
	v_exp_f32_e32 v21, v21
	v_mul_f32_e32 v23, s98, v48
	v_exp_f32_e32 v23, v23
	v_mul_f32_e32 v24, s98, v49
	v_add_f32_e32 v16, 1.0, v16
	v_add_f32_e32 v17, 1.0, v17
	v_add_f32_e32 v18, 1.0, v18
	v_add_f32_e32 v22, 1.0, v22
	v_exp_f32_e32 v24, v24
	v_rcp_f32_e32 v16, v16
	v_rcp_f32_e32 v17, v17
	v_rcp_f32_e32 v18, v18
	v_add_f32_e32 v19, 1.0, v19
	v_add_f32_e32 v21, 1.0, v21
	v_rcp_f32_e32 v22, v22
	v_rcp_f32_e32 v19, v19
	v_rcp_f32_e32 v21, v21
	v_add_f32_e32 v23, 1.0, v23
	v_rcp_f32_e32 v23, v23
	v_add_f32_e32 v24, 1.0, v24
	v_mul_f32_e32 v16, v134, v16
	v_mul_f32_e32 v17, v130, v17
	v_mul_f32_e32 v18, v32, v18
	v_mul_f32_e32 v22, v102, v22
	v_rcp_f32_e32 v24, v24
	v_mul_f32_e32 v16, v16, v78
	v_mul_f32_e32 v17, v17, v55
	v_mul_f32_e32 v18, v18, v54
	v_mul_f32_e32 v19, v33, v19
	v_mul_f32_e32 v21, v106, v21
	v_mul_f32_e32 v22, v22, v27
	v_mul_f32_e32 v19, v19, v57
	v_mul_f32_e32 v21, v21, v26
	v_cvt_pk_bf16_f32 v16, v16, v17
	v_cvt_pk_bf16_f32 v17, v18, v19
	v_cvt_pk_bf16_f32 v18, v21, v22
	v_mul_f32_e32 v22, s98, v215
	v_add_u32_e32 v20, 0x80, v14
	v_mul_f32_e32 v23, v48, v23
	v_exp_f32_e32 v22, v22
	v_mul_f32_e32 v15, v23, v15
	v_mul_f32_e32 v23, v49, v24
	v_mad_i64_i32 v[20:21], s[0:1], v20, s83, v[2:3]
	v_mul_f32_e32 v23, v23, v28
	v_cvt_pk_bf16_f32 v19, v15, v23
	v_lshl_add_u64 v[20:21], v[20:21], 0, v[4:5]
	v_mul_f32_e32 v15, s98, v151
	v_exp_f32_e32 v15, v15
	global_store_dwordx4 v[20:21], v[16:19], off
	v_mul_f32_e32 v20, s98, v118
	v_mul_f32_e32 v21, s98, v119
	v_mul_f32_e32 v17, s98, v150
	v_mul_f32_e32 v18, s98, v155
	v_mul_f32_e32 v19, s98, v120
	v_add_f32_e32 v16, 1.0, v22
	v_exp_f32_e32 v17, v17
	v_exp_f32_e32 v18, v18
	v_exp_f32_e32 v19, v19
	v_exp_f32_e32 v20, v20
	v_exp_f32_e32 v21, v21
	v_mul_f32_e32 v22, s98, v121
	v_exp_f32_e32 v22, v22
	v_add_f32_e32 v15, 1.0, v15
	v_rcp_f32_e32 v15, v15
	v_rcp_f32_e32 v16, v16
	v_add_f32_e32 v17, 1.0, v17
	v_add_f32_e32 v18, 1.0, v18
	v_add_f32_e32 v19, 1.0, v19
	v_add_f32_e32 v20, 1.0, v20
	v_add_f32_e32 v21, 1.0, v21
	v_rcp_f32_e32 v17, v17
	v_rcp_f32_e32 v18, v18
	v_rcp_f32_e32 v19, v19
	v_rcp_f32_e32 v20, v20
	v_rcp_f32_e32 v21, v21
	v_add_f32_e32 v22, 1.0, v22
	v_rcp_f32_e32 v22, v22
	v_mul_f32_e32 v15, v151, v15
	v_mul_f32_e32 v16, v215, v16
	v_mul_f32_e32 v15, v15, v93
	v_mul_f32_e32 v16, v16, v92
	v_mul_f32_e32 v17, v150, v17
	v_mul_f32_e32 v18, v155, v18
	v_mul_f32_e32 v19, v120, v19
	v_mul_f32_e32 v20, v118, v20
	v_mul_f32_e32 v21, v119, v21
	v_mul_f32_e32 v17, v17, v90
	v_mul_f32_e32 v18, v18, v91
	v_mul_f32_e32 v19, v19, v47
	v_mul_f32_e32 v20, v20, v46
	v_mul_f32_e32 v21, v21, v50
	v_mul_f32_e32 v22, v121, v22
; __device__ __forceinline__ unsigned cvt_pk_bf16(float lo, float hi) { unsigned r; asm volatile("v_cvt_pk_bf16_f32 %0, %1, %2" : "=v"(r) : "v"(lo), "v"(hi)); return r; }
; #define PG8_BAR __builtin_amdgcn_s_barrier()
;     __device__ __forceinline__ void operator()(f32x4 (&acc)[2][2][4][2], const Unit& u, int ui, int wr, int wc, int fr_, int fq_) const {
;     ...
;         const int row0 = u.pm * BM + wr * 64 + fr;
; #pragma unroll
;         for (int ai = 0; ai < 2; ++ai)
; #pragma unroll
;             for (int m = 0; m < 4; ++m) { float gv[8];
; #pragma unroll
;                 for (int n = 0; n < 2; ++n)
; #pragma unroll
;                     for (int j = 0; j < 4; ++j) { const float g = acc[ai][0][m][n][j], up = acc[ai][1][m][n][j]; gv[n * 4 + j] = g * __builtin_amdgcn_rcpf(1.0f + __builtin_amdgcn_exp2f(g * -1.4426950408889634f)) * up; }
;                 u32x4 w; w.x = cvt_pk_bf16(gv[0], gv[1]); w.y = cvt_pk_bf16(gv[2], gv[3]); w.z = cvt_pk_bf16(gv[4], gv[5]); w.w = cvt_pk_bf16(gv[6], gv[7]);
;                 *(u32x4*)(G + (size_t)(row0 + ai * HALF + m * 16) * 2816 + fbase) = w; asm volatile("" ::: "memory"); }
; template <class Epi, class Sched, bool ALIGN_EPI = false, bool SP2 = false>
; __device__ __forceinline__ void gemm_phase(PG8_LAS unsigned char* lds, const Gemm g, const Sched& S, const Epi& E) {
;     ...
;         if (!has_next) break;
; #pragma unroll
;         for (int a = 0; a < 2; ++a)
; #pragma unroll
;             for (int b = 0; b < 2; ++b)
; #pragma unroll
;                 for (int m = 0; m < 4; ++m)
; #pragma unroll
;                     for (int n = 0; n < 2; ++n) acc[a][b][m][n] = (f32x4){0.f, 0.f, 0.f, 0.f};
;         cur = nxt; cA = nA; cB = nB; ++ui;
;         if constexpr (ALIGN_EPI) { if (wr == 1) PG8_BAR; }
	v_cvt_pk_bf16_f32 v16, v15, v16
	v_add_u32_e32 v15, 0x90, v14
	v_mul_f32_e32 v22, v22, v51
	v_cvt_pk_bf16_f32 v17, v17, v18
	v_cvt_pk_bf16_f32 v18, v19, v20
	v_cvt_pk_bf16_f32 v19, v21, v22
	v_mad_i64_i32 v[20:21], s[0:1], v15, s83, v[2:3]
	v_lshl_add_u64 v[20:21], v[20:21], 0, v[4:5]
	global_store_dwordx4 v[20:21], v[16:19], off
	v_mul_f32_e32 v20, s98, v114
	v_exp_f32_e32 v20, v20
	v_mul_f32_e32 v19, s98, v116
	v_exp_f32_e32 v19, v19
	v_mul_f32_e32 v15, s98, v147
	v_exp_f32_e32 v15, v15
	v_mul_f32_e32 v22, s98, v149
	v_add_f32_e32 v19, 1.0, v19
	v_rcp_f32_e32 v19, v19
	v_mul_f32_e32 v17, s98, v146
	v_mul_f32_e32 v21, s98, v117
	v_exp_f32_e32 v22, v22
	v_mul_f32_e32 v19, v116, v19
	v_mul_f32_e32 v19, v19, v11
	v_add_f32_e32 v11, 1.0, v20
	v_mul_f32_e32 v20, s98, v115
	v_exp_f32_e32 v20, v20
	v_exp_f32_e32 v17, v17
	v_mul_f32_e32 v18, s98, v148
	v_exp_f32_e32 v21, v21
	v_exp_f32_e32 v18, v18
	v_add_f32_e32 v15, 1.0, v15
	v_rcp_f32_e32 v11, v11
	v_add_f32_e32 v20, 1.0, v20
	v_rcp_f32_e32 v15, v15
	v_add_f32_e32 v16, 1.0, v22
	v_add_f32_e32 v17, 1.0, v17
	v_rcp_f32_e32 v20, v20
	v_add_f32_e32 v21, 1.0, v21
	v_rcp_f32_e32 v16, v16
	v_rcp_f32_e32 v17, v17
	v_add_f32_e32 v18, 1.0, v18
	v_rcp_f32_e32 v21, v21
	v_rcp_f32_e32 v18, v18
	v_mul_f32_e32 v11, v114, v11
	v_mul_f32_e32 v15, v147, v15
	v_mul_f32_e32 v22, v11, v10
	v_mul_f32_e32 v10, v115, v20
	v_mul_f32_e32 v15, v15, v89
	v_mul_f32_e32 v16, v149, v16
	v_mul_f32_e32 v17, v146, v17
	v_mul_f32_e32 v20, v10, v12
	v_mul_f32_e32 v10, v117, v21
	v_mul_f32_e32 v16, v16, v88
	v_mul_f32_e32 v17, v17, v84
	v_mul_f32_e32 v18, v148, v18
	v_mul_f32_e32 v13, v10, v13
	v_cvt_pk_bf16_f32 v10, v15, v16
	v_add_u32_e32 v15, 0xa0, v14
	v_mul_f32_e32 v18, v18, v85
	v_cvt_pk_bf16_f32 v11, v17, v18
	v_mad_i64_i32 v[16:17], s[0:1], v15, s83, v[2:3]
	v_mul_f32_e32 v15, s98, v139
	v_exp_f32_e32 v15, v15
	v_lshl_add_u64 v[16:17], v[16:17], 0, v[4:5]
	v_cvt_pk_bf16_f32 v12, v19, v22
	v_cvt_pk_bf16_f32 v13, v20, v13
	global_store_dwordx4 v[16:17], v[10:13], off
	v_mul_f32_e32 v16, s98, v110
	v_exp_f32_e32 v16, v16
	v_add_f32_e32 v10, 1.0, v15
	v_mul_f32_e32 v15, s98, v112
	v_exp_f32_e32 v15, v15
	v_mul_f32_e32 v18, s98, v141
	v_mul_f32_e32 v17, s98, v113
	v_exp_f32_e32 v18, v18
	v_add_f32_e32 v15, 1.0, v15
	v_rcp_f32_e32 v15, v15
	v_exp_f32_e32 v17, v17
	v_mul_f32_e32 v12, s98, v138
	v_mul_f32_e32 v13, s98, v140
	v_mul_f32_e32 v15, v112, v15
	v_mul_f32_e32 v15, v15, v7
	v_add_f32_e32 v7, 1.0, v16
	v_mul_f32_e32 v16, s98, v111
	v_exp_f32_e32 v16, v16
	v_exp_f32_e32 v12, v12
	v_exp_f32_e32 v13, v13
	v_rcp_f32_e32 v7, v7
	v_add_f32_e32 v16, 1.0, v16
	v_rcp_f32_e32 v10, v10
	v_add_f32_e32 v11, 1.0, v18
	v_rcp_f32_e32 v16, v16
	v_add_f32_e32 v17, 1.0, v17
	v_rcp_f32_e32 v11, v11
	v_rcp_f32_e32 v17, v17
	v_add_f32_e32 v12, 1.0, v12
	v_add_f32_e32 v13, 1.0, v13
	v_mul_f32_e32 v7, v110, v7
	v_mul_f32_e32 v10, v139, v10
	v_rcp_f32_e32 v12, v12
	v_rcp_f32_e32 v13, v13
	v_mul_f32_e32 v18, v7, v6
	v_mul_f32_e32 v6, v111, v16
	v_mul_f32_e32 v10, v10, v87
	v_mul_f32_e32 v11, v141, v11
	v_mul_f32_e32 v16, v6, v8
	v_mul_f32_e32 v6, v113, v17
	v_mul_f32_e32 v11, v11, v86
	v_mul_f32_e32 v9, v6, v9
	v_cvt_pk_bf16_f32 v6, v10, v11
	v_add_u32_e32 v10, 0xb0, v14
	v_mad_i64_i32 v[2:3], s[0:1], v10, s83, v[2:3]
	v_mul_f32_e32 v12, v138, v12
	v_mul_f32_e32 v13, v140, v13
	v_lshl_add_u64 v[2:3], v[2:3], 0, v[4:5]
	v_mul_f32_e32 v12, v12, v82
	v_mul_f32_e32 v13, v13, v83
	v_cvt_pk_bf16_f32 v7, v12, v13
	v_cvt_pk_bf16_f32 v8, v15, v18
	v_cvt_pk_bf16_f32 v9, v16, v9
	global_store_dwordx4 v[2:3], v[6:9], off
	s_andn2_b64 vcc, exec, s[6:7]
	s_mov_b64 s[0:1], -1
	s_cbranch_vccnz .LBB0_1171
	s_andn2_b64 vcc, exec, s[16:17]
	s_cbranch_vccnz .LBB0_1170
	s_barrier
	s_branch .LBB0_1170
